# gMLP: channel rows of the MFMA operand permuted so a lane's two result blocks are contiguous; u/gate loads and output stores widened from 2x8 B to 16 B per lane
# speedup vs baseline: 1.0219x; 1.0170x over previous
; #define LAS __attribute__((address_space(3)))
; __device__ __forceinline__ void gmlp_item(const Params& p, int l, int mc, int g, LAS unsigned char* lds) {
;     ...
;             *(LAS u32x4*)(Vn + c * 272 + oct * 16) = wv;
;         }
;     }
;     __syncthreads();
;     const int ntt = ntok >> 4;
;     f32x4 acc[2][8];
; #pragma unroll
;     for (int tt = 0; tt < 8; ++tt) { acc[0][tt] = (f32x4){0.f, 0.f, 0.f, 0.f}; acc[1][tt] = (f32x4){0.f, 0.f, 0.f, 0.f}; }
; #pragma unroll
;     for (int kk = 0; kk < 4; ++kk) {
;         bf16x8 a[2];
; #pragma unroll
;         for (int ct = 0; ct < 2; ++ct) a[ct] = *(const LAS bf16x8*)(Vn + (w * 32 + ct * 16 + fr) * 272 + (kk * 32 + fq * 8) * 2);
; #pragma unroll
;         for (int tt = 0; tt < 8; ++tt) {
;             if ((tt >> 1) >= kk && tt < ntt) {
;                 const bf16x8 bw = *(const LAS bf16x8*)(Wl + (tt * 16 + fr) * 272 + (kk * 32 + fq * 8) * 2);
; #pragma unroll
;                 for (int ct = 0; ct < 2; ++ct) acc[ct][tt] = __builtin_amdgcn_mfma_f32_16x16x32_bf16(a[ct], bw, acc[ct][tt], 0, 0, 0);
;             }
.LBB0_746:
	s_or_b64 exec, exec, s[18:19]
	v_lshlrev_b32_e32 v84, 5, v27
	v_and_b32_e32 v0, 12, v161
	v_lshlrev_b32_e32 v0, 1, v0
	v_and_or_b32 v0, v161, 3, v0
	v_or_b32_e32 v0, v84, v0
	v_readlane_b32 s7, v252, 41
	s_waitcnt lgkmcnt(7)
	v_add_u32_e32 v2, 0, v25
	v_mul_lo_u32 v0, v0, s30
	v_add_u32_e32 v3, s7, v25
	v_add_u32_e32 v85, v2, v0
	v_mad_u32_u24 v2, v161, s30, v3
	ds_write_b128 v31, v[18:21] offset:56320
	s_waitcnt lgkmcnt(0)
	s_barrier
	ds_read_b128 v[4:7], v85 offset:4096
	ds_read_b128 v[36:39], v85 offset:5184
	ds_read_b128 v[8:11], v2
	s_waitcnt lgkmcnt(0)
	v_mfma_f32_16x16x32_bf16 v[64:67], v[4:7], v[8:11], 0
	s_mov_b32 s76, s77
	v_mul_u32_u24_e32 v0, 0x110, v161
	s_mov_b32 s78, s77
	v_mfma_f32_16x16x32_bf16 v[60:63], v[36:39], v[8:11], 0
	ds_read_b128 v[8:11], v2 offset:4352
	s_mov_b32 s79, s77
	v_mov_b64_e32 v[28:29], s[76:77]
	s_waitcnt lgkmcnt(0)
	v_mfma_f32_16x16x32_bf16 v[56:59], v[4:7], v[8:11], 0
	v_mov_b64_e32 v[32:33], s[76:77]
	v_mov_b64_e32 v[30:31], s[78:79]
	s_andn2_b64 vcc, exec, s[16:17]
	v_mfma_f32_16x16x32_bf16 v[52:55], v[36:39], v[8:11], 0
	ds_read_b128 v[8:11], v2 offset:8704
	v_add_u32_e32 v86, v3, v0
	v_mov_b64_e32 v[34:35], s[78:79]
	s_waitcnt lgkmcnt(0)
	v_mfma_f32_16x16x32_bf16 v[40:43], v[4:7], v[8:11], 0
	v_mfma_f32_16x16x32_bf16 v[44:47], v[36:39], v[8:11], 0
	ds_read_b128 v[8:11], v2 offset:13056
	v_cndmask_b32_e64 v2, 0, 1, s[16:17]
	v_cmp_ne_u32_e64 s[38:39], 1, v2
	s_waitcnt lgkmcnt(0)
	v_mfma_f32_16x16x32_bf16 v[68:71], v[4:7], v[8:11], 0
	v_mfma_f32_16x16x32_bf16 v[72:75], v[36:39], v[8:11], 0
	s_cbranch_vccnz .LBB0_748
	ds_read_b128 v[8:11], v86 offset:17408
	s_waitcnt lgkmcnt(0)
	v_mfma_f32_16x16x32_bf16 v[32:35], v[4:7], v[8:11], 0
	v_mfma_f32_16x16x32_bf16 v[28:31], v[36:39], v[8:11], 0

; #define LAS __attribute__((address_space(3)))
; __device__ __forceinline__ void gmlp_item(const Params& p, int l, int mc, int g, LAS unsigned char* lds) {
;     ...
;     for (int kk = 0; kk < 4; ++kk) {
;         bf16x8 a[2];
; #pragma unroll
;         for (int ct = 0; ct < 2; ++ct) a[ct] = *(const LAS bf16x8*)(Vn + (w * 32 + ct * 16 + fr) * 272 + (kk * 32 + fq * 8) * 2);
; #pragma unroll
;         for (int tt = 0; tt < 8; ++tt) {
;             if ((tt >> 1) >= kk && tt < ntt) {
;                 const bf16x8 bw = *(const LAS bf16x8*)(Wl + (tt * 16 + fr) * 272 + (kk * 32 + fq * 8) * 2);
; #pragma unroll
;                 for (int ct = 0; ct < 2; ++ct) acc[ct][tt] = __builtin_amdgcn_mfma_f32_16x16x32_bf16(a[ct], bw, acc[ct][tt], 0, 0, 0);
;             }
.LBB0_755:
	ds_read_b128 v[76:79], v85 offset:4160
	ds_read_b128 v[80:83], v85 offset:5248
	ds_read_b128 v[36:39], v86 offset:8768
	s_and_b64 vcc, exec, s[38:39]
	s_waitcnt lgkmcnt(0)
	v_mfma_f32_16x16x32_bf16 v[48:51], v[76:79], v[36:39], v[40:43]
	v_mfma_f32_16x16x32_bf16 v[44:47], v[80:83], v[36:39], v[44:47]
	ds_read_b128 v[36:39], v86 offset:13120
	s_waitcnt lgkmcnt(0)
	v_mfma_f32_16x16x32_bf16 v[40:43], v[76:79], v[36:39], v[68:71]
	v_mfma_f32_16x16x32_bf16 v[36:39], v[80:83], v[36:39], v[72:75]
	s_cbranch_vccz .LBB0_775
	s_and_b64 vcc, exec, s[38:39]
	s_cbranch_vccz .LBB0_776

; #define LAS __attribute__((address_space(3)))
; __device__ __forceinline__ void gmlp_item(const Params& p, int l, int mc, int g, LAS unsigned char* lds) {
;     ...
;     for (int kk = 0; kk < 4; ++kk) {
;         bf16x8 a[2];
; #pragma unroll
;         for (int ct = 0; ct < 2; ++ct) a[ct] = *(const LAS bf16x8*)(Vn + (w * 32 + ct * 16 + fr) * 272 + (kk * 32 + fq * 8) * 2);
; #pragma unroll
;         for (int tt = 0; tt < 8; ++tt) {
;             if ((tt >> 1) >= kk && tt < ntt) {
;                 const bf16x8 bw = *(const LAS bf16x8*)(Wl + (tt * 16 + fr) * 272 + (kk * 32 + fq * 8) * 2);
; #pragma unroll
;                 for (int ct = 0; ct < 2; ++ct) acc[ct][tt] = __builtin_amdgcn_mfma_f32_16x16x32_bf16(a[ct], bw, acc[ct][tt], 0, 0, 0);
;             }
.LBB0_759:
	ds_read_b128 v[68:71], v85 offset:4224
	ds_read_b128 v[72:75], v85 offset:5312
	s_and_b64 vcc, exec, s[38:39]
	s_cbranch_vccz .LBB0_779

; #define LAS __attribute__((address_space(3)))
; __device__ __forceinline__ void gmlp_item(const Params& p, int l, int mc, int g, LAS unsigned char* lds) {
;     ...
;     for (int kk = 0; kk < 4; ++kk) {
;         bf16x8 a[2];
; #pragma unroll
;         for (int ct = 0; ct < 2; ++ct) a[ct] = *(const LAS bf16x8*)(Vn + (w * 32 + ct * 16 + fr) * 272 + (kk * 32 + fq * 8) * 2);
; #pragma unroll
;         for (int tt = 0; tt < 8; ++tt) {
;             if ((tt >> 1) >= kk && tt < ntt) {
;                 const bf16x8 bw = *(const LAS bf16x8*)(Wl + (tt * 16 + fr) * 272 + (kk * 32 + fq * 8) * 2);
; #pragma unroll
;                 for (int ct = 0; ct < 2; ++ct) acc[ct][tt] = __builtin_amdgcn_mfma_f32_16x16x32_bf16(a[ct], bw, acc[ct][tt], 0, 0, 0);
;             }
.LBB0_763:
	s_waitcnt lgkmcnt(1)
	ds_read_b128 v[68:71], v85 offset:4288
	s_waitcnt lgkmcnt(1)
	ds_read_b128 v[72:75], v85 offset:5376
	s_and_b64 vcc, exec, s[38:39]
	s_cbranch_vccz .LBB0_783

; __device__ __forceinline__ unsigned cvt_pk_bf16(float lo, float hi) { unsigned r; asm("v_cvt_pk_bf16_f32 %0, %1, %2" : "=v"(r) : "v"(lo), "v"(hi)); return r; }
; __device__ __forceinline__ float bflo(unsigned w) { return __uint_as_float(w << 16); }
; __device__ __forceinline__ float bfhi(unsigned w) { return __uint_as_float(w & 0xffff0000u); }
; __device__ __forceinline__ float silu(float x) { return x / (1.f + __expf(-x)); }
; __device__ __forceinline__ void gmlp_item(const Params& p, int l, int mc, int g, LAS unsigned char* lds) {
;     ...
;     const float* bsp = p.b_s + (size_t)(l * 4 + g) * 128;
; #pragma unroll
;     for (int tt = 0; tt < 8; ++tt) {
;         if (tt < ntt) {
;             const int tok = tok0 + tt * 16 + fr; const float bs = bsp[tt * 16 + fr];
; #pragma unroll
;             for (int ct = 0; ct < 2; ++ct) {
;                 const int cb = g * 256 + w * 32 + ct * 16 + fq * 4;
;                 const u32x2 uu = *(const u32x2*)((const u16*)(ws + WS_ZU) + (size_t)tok * 1024 + cb);
;                 const u32x2 gg = *(const u32x2*)((const u16*)(ws + WS_ZGB) + (size_t)tok * 1024 + cb);
;                 const float o0 = bflo(uu.x) * (acc[ct][tt][0] + bs) * silu(bflo(gg.x));
;                 const float o1 = bfhi(uu.x) * (acc[ct][tt][1] + bs) * silu(bfhi(gg.x));
;                 const float o2 = bflo(uu.y) * (acc[ct][tt][2] + bs) * silu(bflo(gg.y));
;                 const float o3 = bfhi(uu.y) * (acc[ct][tt][3] + bs) * silu(bfhi(gg.y));
;                 u32x2 wv; wv.x = cvt_pk_bf16(o0, o1); wv.y = cvt_pk_bf16(o2, o3);
;                 *(u32x2*)((u16*)(ws + WS_OBUF) + (size_t)tok * 2048 + 1024 + cb) = wv;
.LBB0_766:
	v_or_b32_e32 v0, s2, v161
	v_add_u32_e32 v2, s6, v84
	v_lshrrev_b32_e32 v3, 1, v160
	s_waitcnt lgkmcnt(0)
	v_and_or_b32 v74, v3, 24, v2
	v_lshlrev_b64 v[2:3], 11, v[0:1]
	v_lshl_add_u64 v[72:73], s[86:87], 0, v[2:3]
	v_lshl_add_u64 v[76:77], s[34:35], 0, v[2:3]
	v_lshlrev_b64 v[2:3], 12, v[0:1]
	s_lshl_b64 s[0:1], s[0:1], 9
	v_lshl_add_u64 v[2:3], s[58:59], 0, v[2:3]
	s_mov_b64 s[10:11], 0x2958c800
	v_ashrrev_i32_e32 v75, 31, v74
	s_add_u32 s0, s74, s0
	v_lshl_add_u64 v[70:71], v[2:3], 0, s[10:11]
	v_lshlrev_b64 v[2:3], 1, v[74:75]
	s_addc_u32 s1, s75, s1
	v_lshlrev_b32_e32 v68, 2, v161
	v_lshl_add_u64 v[78:79], v[72:73], 0, v[2:3]
	v_lshl_add_u64 v[72:73], v[76:77], 0, v[2:3]
	s_mov_b64 s[98:99], 0x8000
	v_mov_b32_e32 v224, v78
	v_mov_b32_e32 v225, v79
	v_mov_b32_e32 v226, v72
	v_mov_b32_e32 v227, v73
	global_load_dword v178, v68, s[0:1]
	global_load_dwordx4 v[182:185], v[224:225], off
	global_load_dwordx4 v[208:211], v[226:227], off
	v_lshl_add_u64 v[224:225], v[224:225], 0, s[98:99]
	v_lshl_add_u64 v[226:227], v[226:227], 0, s[98:99]
	global_load_dword v179, v68, s[0:1] offset:64
	global_load_dwordx4 v[186:189], v[224:225], off
	global_load_dwordx4 v[212:215], v[226:227], off
	v_lshl_add_u64 v[224:225], v[224:225], 0, s[98:99]
	v_lshl_add_u64 v[226:227], v[226:227], 0, s[98:99]
	global_load_dword v180, v68, s[0:1] offset:128
	global_load_dwordx4 v[190:193], v[224:225], off
	global_load_dwordx4 v[216:219], v[226:227], off
	v_lshl_add_u64 v[224:225], v[224:225], 0, s[98:99]
	v_lshl_add_u64 v[226:227], v[226:227], 0, s[98:99]
	global_load_dword v181, v68, s[0:1] offset:192
	global_load_dwordx4 v[194:197], v[224:225], off
	global_load_dwordx4 v[220:223], v[226:227], off
	v_lshl_add_u64 v[224:225], v[224:225], 0, s[98:99]
	v_lshl_add_u64 v[226:227], v[226:227], 0, s[98:99]
	v_mov_b32_e32 v228, v224
	v_mov_b32_e32 v229, v225
	v_mov_b32_e32 v230, v226
	v_mov_b32_e32 v231, v227
	v_mov_b32_e32 v232, v68
	v_mov_b32_e32 v233, 0
	v_lshl_add_u64 v[232:233], s[0:1], 0, v[232:233]
	v_lshl_add_u64 v[232:233], v[232:233], 0, 64
	v_lshl_add_u64 v[232:233], v[232:233], 0, 64
	v_lshl_add_u64 v[232:233], v[232:233], 0, 64
	v_lshl_add_u64 v[232:233], v[232:233], 0, 64
	s_waitcnt vmcnt(11)
	v_mov_b32_e32 v69, v178
	v_add_f32_e32 v64, v64, v69
	s_waitcnt vmcnt(10)
	v_mov_b32_e32 v80, v182
	v_mov_b32_e32 v81, v183
	v_lshlrev_b32_e32 v75, 16, v80
	v_mul_f32_e32 v64, v64, v75
	s_waitcnt vmcnt(9)
	v_mov_b32_e32 v76, v208
	v_mov_b32_e32 v77, v209
	v_lshlrev_b32_e32 v75, 16, v76
	v_mul_f32_e32 v82, 0xbfb8aa3b, v75
	v_exp_f32_e32 v82, v82
	v_add_f32_e32 v65, v65, v69
	v_add_f32_e32 v66, v66, v69
	v_add_f32_e32 v67, v67, v69
	v_add_f32_e32 v82, 1.0, v82
	v_div_scale_f32 v83, s[6:7], v82, v82, v75
	v_rcp_f32_e32 v84, v83
	v_add_f32_e32 v60, v60, v69
	v_add_f32_e32 v61, v61, v69
	v_add_f32_e32 v62, v62, v69
	v_fma_f32 v85, -v83, v84, 1.0
	v_fmac_f32_e32 v84, v85, v84
	v_div_scale_f32 v85, vcc, v75, v82, v75
	v_mul_f32_e32 v86, v85, v84
	v_fma_f32 v87, -v83, v86, v85
	v_fmac_f32_e32 v86, v87, v84
	v_fma_f32 v83, -v83, v86, v85
	v_div_fmas_f32 v83, v83, v84, v86
	v_div_fixup_f32 v75, v83, v82, v75
	v_mul_f32_e32 v64, v64, v75
	v_and_b32_e32 v75, 0xffff0000, v80
	v_mul_f32_e32 v65, v65, v75
	v_and_b32_e32 v75, 0xffff0000, v76
	v_mul_f32_e32 v76, 0xbfb8aa3b, v75
	v_exp_f32_e32 v76, v76
	v_add_f32_e32 v63, v63, v69
	v_add_f32_e32 v76, 1.0, v76
	v_div_scale_f32 v80, s[6:7], v76, v76, v75
	v_rcp_f32_e32 v82, v80
	s_nop 0
	v_fma_f32 v83, -v80, v82, 1.0
	v_fmac_f32_e32 v82, v83, v82
	v_div_scale_f32 v83, vcc, v75, v76, v75
	v_mul_f32_e32 v84, v83, v82
	v_fma_f32 v85, -v80, v84, v83
	v_fmac_f32_e32 v84, v85, v82
	v_fma_f32 v80, -v80, v84, v83
	v_div_fmas_f32 v80, v80, v82, v84
	v_div_fixup_f32 v75, v80, v76, v75
	v_mul_f32_e32 v65, v65, v75
	v_lshlrev_b32_e32 v75, 16, v81
	v_mul_f32_e32 v66, v66, v75
	v_lshlrev_b32_e32 v75, 16, v77
	v_mul_f32_e32 v76, 0xbfb8aa3b, v75
	v_exp_f32_e32 v76, v76
	v_cvt_pk_bf16_f32 v64, v64, v65
	s_nop 0
	v_add_f32_e32 v76, 1.0, v76
	v_div_scale_f32 v80, s[6:7], v76, v76, v75
	v_rcp_f32_e32 v82, v80
	s_nop 0
	v_fma_f32 v83, -v80, v82, 1.0
	v_fmac_f32_e32 v82, v83, v82
	v_div_scale_f32 v83, vcc, v75, v76, v75
	v_mul_f32_e32 v84, v83, v82
	v_fma_f32 v85, -v80, v84, v83
	v_fmac_f32_e32 v84, v85, v82
	v_fma_f32 v80, -v80, v84, v83
	v_div_fmas_f32 v80, v80, v82, v84
	v_div_fixup_f32 v75, v80, v76, v75
	v_mul_f32_e32 v66, v66, v75
	v_and_b32_e32 v75, 0xffff0000, v81
	v_mul_f32_e32 v67, v67, v75
	v_and_b32_e32 v75, 0xffff0000, v77
	v_mul_f32_e32 v76, 0xbfb8aa3b, v75
	v_exp_f32_e32 v76, v76
	s_nop 0
	v_add_f32_e32 v76, 1.0, v76
	v_div_scale_f32 v77, s[6:7], v76, v76, v75
	v_rcp_f32_e32 v80, v77
	s_nop 0
	v_fma_f32 v81, -v77, v80, 1.0
	v_fmac_f32_e32 v80, v81, v80
	v_div_scale_f32 v81, vcc, v75, v76, v75
	v_mul_f32_e32 v82, v81, v80
	v_fma_f32 v83, -v77, v82, v81
	v_fmac_f32_e32 v82, v83, v80
	v_fma_f32 v77, -v77, v82, v81
	v_div_fmas_f32 v77, v77, v80, v82
	v_div_fixup_f32 v75, v77, v76, v75
	v_mul_f32_e32 v67, v67, v75
	v_cvt_pk_bf16_f32 v65, v66, v67
	v_lshl_add_u64 v[66:67], v[70:71], 0, v[2:3]
	v_mov_b32_e32 v104, v64
	v_mov_b32_e32 v105, v65
	s_nop 0
	v_or_b32_e32 v64, 4, v74
	v_ashrrev_i32_e32 v65, 31, v64
	s_waitcnt vmcnt(10)
	v_mov_b32_e32 v66, v184
	v_mov_b32_e32 v67, v185
	v_lshlrev_b32_e32 v74, 16, v66
	v_mul_f32_e32 v60, v60, v74
	s_waitcnt vmcnt(9)
; __device__ __forceinline__ unsigned cvt_pk_bf16(float lo, float hi) { unsigned r; asm("v_cvt_pk_bf16_f32 %0, %1, %2" : "=v"(r) : "v"(lo), "v"(hi)); return r; }
; __device__ __forceinline__ float bflo(unsigned w) { return __uint_as_float(w << 16); }
; __device__ __forceinline__ float bfhi(unsigned w) { return __uint_as_float(w & 0xffff0000u); }
; __device__ __forceinline__ float silu(float x) { return x / (1.f + __expf(-x)); }
; __device__ __forceinline__ void gmlp_item(const Params& p, int l, int mc, int g, LAS unsigned char* lds) {
;     ...
;     const float* bsp = p.b_s + (size_t)(l * 4 + g) * 128;
; #pragma unroll
;     for (int tt = 0; tt < 8; ++tt) {
;         if (tt < ntt) {
;             const int tok = tok0 + tt * 16 + fr; const float bs = bsp[tt * 16 + fr];
; #pragma unroll
;             for (int ct = 0; ct < 2; ++ct) {
;                 const int cb = g * 256 + w * 32 + ct * 16 + fq * 4;
;                 const u32x2 uu = *(const u32x2*)((const u16*)(ws + WS_ZU) + (size_t)tok * 1024 + cb);
;                 const u32x2 gg = *(const u32x2*)((const u16*)(ws + WS_ZGB) + (size_t)tok * 1024 + cb);
;                 const float o0 = bflo(uu.x) * (acc[ct][tt][0] + bs) * silu(bflo(gg.x));
;                 const float o1 = bfhi(uu.x) * (acc[ct][tt][1] + bs) * silu(bfhi(gg.x));
;                 const float o2 = bflo(uu.y) * (acc[ct][tt][2] + bs) * silu(bflo(gg.y));
;                 const float o3 = bfhi(uu.y) * (acc[ct][tt][3] + bs) * silu(bfhi(gg.y));
;                 u32x2 wv; wv.x = cvt_pk_bf16(o0, o1); wv.y = cvt_pk_bf16(o2, o3);
;                 *(u32x2*)((u16*)(ws + WS_OBUF) + (size_t)tok * 2048 + 1024 + cb) = wv;
	v_mov_b32_e32 v72, v210
	v_mov_b32_e32 v73, v211
	v_lshlrev_b32_e32 v74, 16, v72
	v_mul_f32_e32 v75, 0xbfb8aa3b, v74
	v_exp_f32_e32 v75, v75
	v_and_b32_e32 v66, 0xffff0000, v66
	v_mul_f32_e32 v61, v61, v66
	v_and_b32_e32 v66, 0xffff0000, v72
	v_add_f32_e32 v75, 1.0, v75
	v_div_scale_f32 v76, s[6:7], v75, v75, v74
	v_rcp_f32_e32 v77, v76
	v_mul_f32_e32 v72, 0xbfb8aa3b, v66
	v_exp_f32_e32 v72, v72
	v_fma_f32 v78, -v76, v77, 1.0
	v_fmac_f32_e32 v77, v78, v77
	v_div_scale_f32 v78, vcc, v74, v75, v74
	v_mul_f32_e32 v79, v78, v77
	v_fma_f32 v80, -v76, v79, v78
	v_fmac_f32_e32 v79, v80, v77
	v_fma_f32 v76, -v76, v79, v78
	v_div_fmas_f32 v76, v76, v77, v79
	v_div_fixup_f32 v74, v76, v75, v74
	v_add_f32_e32 v72, 1.0, v72
	v_mul_f32_e32 v60, v60, v74
	v_div_scale_f32 v74, s[6:7], v72, v72, v66
	v_rcp_f32_e32 v75, v74
	s_nop 0
	v_fma_f32 v76, -v74, v75, 1.0
	v_fmac_f32_e32 v75, v76, v75
	v_div_scale_f32 v76, vcc, v66, v72, v66
	v_mul_f32_e32 v77, v76, v75
	v_fma_f32 v78, -v74, v77, v76
	v_fmac_f32_e32 v77, v78, v75
	v_fma_f32 v74, -v74, v77, v76
	v_div_fmas_f32 v74, v74, v75, v77
	v_div_fixup_f32 v66, v74, v72, v66
	v_mul_f32_e32 v61, v61, v66
	v_lshlrev_b32_e32 v66, 16, v67
	v_mul_f32_e32 v62, v62, v66
	v_lshlrev_b32_e32 v66, 16, v73
	v_mul_f32_e32 v72, 0xbfb8aa3b, v66
	v_exp_f32_e32 v72, v72
	s_nop 0
	v_add_f32_e32 v72, 1.0, v72
	v_div_scale_f32 v74, s[6:7], v72, v72, v66
	v_rcp_f32_e32 v75, v74
	s_nop 0
	v_fma_f32 v76, -v74, v75, 1.0
	v_fmac_f32_e32 v75, v76, v75
	v_div_scale_f32 v76, vcc, v66, v72, v66
	v_mul_f32_e32 v77, v76, v75
	v_fma_f32 v78, -v74, v77, v76
	v_fmac_f32_e32 v77, v78, v75
	v_fma_f32 v74, -v74, v77, v76
	v_div_fmas_f32 v74, v74, v75, v77
	v_div_fixup_f32 v66, v74, v72, v66
	v_mul_f32_e32 v66, v62, v66
	v_and_b32_e32 v62, 0xffff0000, v67
	v_mul_f32_e32 v62, v63, v62
	v_and_b32_e32 v63, 0xffff0000, v73
	v_mul_f32_e32 v67, 0xbfb8aa3b, v63
	v_exp_f32_e32 v67, v67
	s_nop 0
	v_add_f32_e32 v67, 1.0, v67
	v_div_scale_f32 v69, s[6:7], v67, v67, v63
	v_rcp_f32_e32 v72, v69
	s_nop 0
	v_fma_f32 v73, -v69, v72, 1.0
	v_fmac_f32_e32 v72, v73, v72
	v_div_scale_f32 v73, vcc, v63, v67, v63
	v_mul_f32_e32 v74, v73, v72
	v_fma_f32 v75, -v69, v74, v73
	v_fmac_f32_e32 v74, v75, v72
	v_fma_f32 v69, -v69, v74, v73
	v_div_fmas_f32 v69, v69, v72, v74
	v_div_fixup_f32 v63, v69, v67, v63
	v_mul_f32_e32 v63, v62, v63
	v_cvt_pk_bf16_f32 v62, v60, v61
	v_lshlrev_b64 v[60:61], 1, v[64:65]
	v_cvt_pk_bf16_f32 v63, v66, v63
	v_lshl_add_u64 v[64:65], v[70:71], 0, v[60:61]
	v_mov_b32_e32 v106, v62
	v_mov_b32_e32 v107, v63
	global_store_dwordx4 v[64:65], v[104:107], off offset:-8
	v_or_b32_e32 v62, 16, v0
	v_mov_b32_e32 v63, v1
	v_lshlrev_b64 v[64:65], 11, v[62:63]
	v_lshl_add_u64 v[70:71], s[86:87], 0, v[64:65]
	v_lshl_add_u64 v[64:65], s[34:35], 0, v[64:65]
	v_lshl_add_u64 v[70:71], v[70:71], 0, v[2:3]
	v_lshl_add_u64 v[64:65], v[64:65], 0, v[2:3]
	v_lshlrev_b64 v[62:63], 12, v[62:63]
	v_lshl_add_u64 v[62:63], s[58:59], 0, v[62:63]
	v_lshl_add_u64 v[62:63], v[62:63], 0, s[10:11]
	s_waitcnt vmcnt(9)
	v_mov_b32_e32 v66, v179
	v_add_f32_e32 v56, v56, v66
	s_waitcnt vmcnt(8)
	v_mov_b32_e32 v72, v186
	v_mov_b32_e32 v73, v187
	v_lshlrev_b32_e32 v67, 16, v72
	v_mul_f32_e32 v56, v56, v67
	s_waitcnt vmcnt(7)
	v_mov_b32_e32 v74, v212
	v_mov_b32_e32 v75, v213
	v_lshlrev_b32_e32 v67, 16, v74
	v_mul_f32_e32 v69, 0xbfb8aa3b, v67
	v_exp_f32_e32 v69, v69
	v_add_f32_e32 v57, v57, v66
	v_add_f32_e32 v58, v58, v66
	v_add_f32_e32 v59, v59, v66
	v_add_f32_e32 v69, 1.0, v69
	v_div_scale_f32 v76, s[6:7], v69, v69, v67
	v_rcp_f32_e32 v77, v76
	v_add_f32_e32 v52, v52, v66
	v_add_f32_e32 v53, v53, v66
	v_add_f32_e32 v54, v54, v66
	v_fma_f32 v78, -v76, v77, 1.0
	v_fmac_f32_e32 v77, v78, v77
	v_div_scale_f32 v78, vcc, v67, v69, v67
	v_mul_f32_e32 v79, v78, v77
	v_fma_f32 v80, -v76, v79, v78
	v_fmac_f32_e32 v79, v80, v77
	v_fma_f32 v76, -v76, v79, v78
	v_div_fmas_f32 v76, v76, v77, v79
	v_div_fixup_f32 v67, v76, v69, v67
	v_mul_f32_e32 v56, v56, v67
	v_and_b32_e32 v67, 0xffff0000, v72
	v_mul_f32_e32 v57, v57, v67
	v_and_b32_e32 v67, 0xffff0000, v74
	v_mul_f32_e32 v69, 0xbfb8aa3b, v67
	v_exp_f32_e32 v69, v69
	v_add_f32_e32 v55, v55, v66
	v_add_f32_e32 v69, 1.0, v69
	v_div_scale_f32 v72, s[6:7], v69, v69, v67
	v_rcp_f32_e32 v74, v72
	s_nop 0
	v_fma_f32 v76, -v72, v74, 1.0
	v_fmac_f32_e32 v74, v76, v74
	v_div_scale_f32 v76, vcc, v67, v69, v67
	v_mul_f32_e32 v77, v76, v74
	v_fma_f32 v78, -v72, v77, v76
	v_fmac_f32_e32 v77, v78, v74
	v_fma_f32 v72, -v72, v77, v76
	v_div_fmas_f32 v72, v72, v74, v77
	v_div_fixup_f32 v67, v72, v69, v67
	v_mul_f32_e32 v57, v57, v67
	v_lshlrev_b32_e32 v67, 16, v73
	v_mul_f32_e32 v58, v58, v67
	v_lshlrev_b32_e32 v67, 16, v75
	v_mul_f32_e32 v69, 0xbfb8aa3b, v67
	v_exp_f32_e32 v69, v69
	v_cvt_pk_bf16_f32 v56, v56, v57
	s_nop 0
	v_add_f32_e32 v69, 1.0, v69
	v_div_scale_f32 v72, s[6:7], v69, v69, v67
	v_rcp_f32_e32 v74, v72
	s_nop 0
	v_fma_f32 v76, -v72, v74, 1.0
	v_fmac_f32_e32 v74, v76, v74
	v_div_scale_f32 v76, vcc, v67, v69, v67
	v_mul_f32_e32 v77, v76, v74
	v_fma_f32 v78, -v72, v77, v76
	v_fmac_f32_e32 v77, v78, v74
	v_fma_f32 v72, -v72, v77, v76
	v_div_fmas_f32 v72, v72, v74, v77
	v_div_fixup_f32 v67, v72, v69, v67
	v_mul_f32_e32 v58, v58, v67
	v_and_b32_e32 v67, 0xffff0000, v73
	v_mul_f32_e32 v59, v59, v67
	v_and_b32_e32 v67, 0xffff0000, v75
	v_mul_f32_e32 v69, 0xbfb8aa3b, v67
	v_exp_f32_e32 v69, v69
	s_nop 0
	v_add_f32_e32 v69, 1.0, v69
	v_div_scale_f32 v72, s[6:7], v69, v69, v67
	v_rcp_f32_e32 v73, v72
	s_nop 0
	v_fma_f32 v74, -v72, v73, 1.0
	v_fmac_f32_e32 v73, v74, v73
	v_div_scale_f32 v74, vcc, v67, v69, v67
	v_mul_f32_e32 v75, v74, v73
	v_fma_f32 v76, -v72, v75, v74
	v_fmac_f32_e32 v75, v76, v73
	v_fma_f32 v72, -v72, v75, v74
	v_div_fmas_f32 v72, v72, v73, v75
	v_div_fixup_f32 v67, v72, v69, v67
	v_mul_f32_e32 v59, v59, v67
	v_cvt_pk_bf16_f32 v57, v58, v59
	v_lshl_add_u64 v[58:59], v[62:63], 0, v[2:3]
	v_mov_b32_e32 v104, v56
	v_mov_b32_e32 v105, v57
	s_nop 0
	s_waitcnt vmcnt(8)
; __device__ __forceinline__ unsigned cvt_pk_bf16(float lo, float hi) { unsigned r; asm("v_cvt_pk_bf16_f32 %0, %1, %2" : "=v"(r) : "v"(lo), "v"(hi)); return r; }
; __device__ __forceinline__ float bflo(unsigned w) { return __uint_as_float(w << 16); }
; __device__ __forceinline__ float bfhi(unsigned w) { return __uint_as_float(w & 0xffff0000u); }
; __device__ __forceinline__ float silu(float x) { return x / (1.f + __expf(-x)); }
; __device__ __forceinline__ void gmlp_item(const Params& p, int l, int mc, int g, LAS unsigned char* lds) {
;     ...
;     const float* bsp = p.b_s + (size_t)(l * 4 + g) * 128;
; #pragma unroll
;     for (int tt = 0; tt < 8; ++tt) {
;         if (tt < ntt) {
;             const int tok = tok0 + tt * 16 + fr; const float bs = bsp[tt * 16 + fr];
; #pragma unroll
;             for (int ct = 0; ct < 2; ++ct) {
;                 const int cb = g * 256 + w * 32 + ct * 16 + fq * 4;
;                 const u32x2 uu = *(const u32x2*)((const u16*)(ws + WS_ZU) + (size_t)tok * 1024 + cb);
;                 const u32x2 gg = *(const u32x2*)((const u16*)(ws + WS_ZGB) + (size_t)tok * 1024 + cb);
;                 const float o0 = bflo(uu.x) * (acc[ct][tt][0] + bs) * silu(bflo(gg.x));
;                 const float o1 = bfhi(uu.x) * (acc[ct][tt][1] + bs) * silu(bfhi(gg.x));
;                 const float o2 = bflo(uu.y) * (acc[ct][tt][2] + bs) * silu(bflo(gg.y));
;                 const float o3 = bfhi(uu.y) * (acc[ct][tt][3] + bs) * silu(bfhi(gg.y));
;                 u32x2 wv; wv.x = cvt_pk_bf16(o0, o1); wv.y = cvt_pk_bf16(o2, o3);
;                 *(u32x2*)((u16*)(ws + WS_OBUF) + (size_t)tok * 2048 + 1024 + cb) = wv;
	v_mov_b32_e32 v56, v188
	v_mov_b32_e32 v57, v189
	v_lshlrev_b32_e32 v64, 16, v56
	v_mul_f32_e32 v52, v52, v64
	s_waitcnt vmcnt(7)
	v_mov_b32_e32 v58, v214
	v_mov_b32_e32 v59, v215
	v_lshlrev_b32_e32 v64, 16, v58
	v_mul_f32_e32 v65, 0xbfb8aa3b, v64
	v_exp_f32_e32 v65, v65
	v_and_b32_e32 v56, 0xffff0000, v56
	v_mul_f32_e32 v53, v53, v56
	v_and_b32_e32 v56, 0xffff0000, v58
	v_add_f32_e32 v65, 1.0, v65
	v_div_scale_f32 v67, s[6:7], v65, v65, v64
	v_rcp_f32_e32 v69, v67
	v_mul_f32_e32 v58, 0xbfb8aa3b, v56
	v_exp_f32_e32 v58, v58
	v_fma_f32 v70, -v67, v69, 1.0
	v_fmac_f32_e32 v69, v70, v69
	v_div_scale_f32 v70, vcc, v64, v65, v64
	v_mul_f32_e32 v71, v70, v69
	v_fma_f32 v72, -v67, v71, v70
	v_fmac_f32_e32 v71, v72, v69
	v_fma_f32 v67, -v67, v71, v70
	v_div_fmas_f32 v67, v67, v69, v71
	v_div_fixup_f32 v64, v67, v65, v64
	v_add_f32_e32 v58, 1.0, v58
	v_mul_f32_e32 v52, v52, v64
	v_div_scale_f32 v64, s[6:7], v58, v58, v56
	v_rcp_f32_e32 v65, v64
	s_nop 0
	v_fma_f32 v67, -v64, v65, 1.0
	v_fmac_f32_e32 v65, v67, v65
	v_div_scale_f32 v67, vcc, v56, v58, v56
	v_mul_f32_e32 v69, v67, v65
	v_fma_f32 v70, -v64, v69, v67
	v_fmac_f32_e32 v69, v70, v65
	v_fma_f32 v64, -v64, v69, v67
	v_div_fmas_f32 v64, v64, v65, v69
	v_div_fixup_f32 v56, v64, v58, v56
	v_mul_f32_e32 v53, v53, v56
	v_lshlrev_b32_e32 v56, 16, v57
	v_mul_f32_e32 v54, v54, v56
	v_lshlrev_b32_e32 v56, 16, v59
	v_mul_f32_e32 v58, 0xbfb8aa3b, v56
	v_exp_f32_e32 v58, v58
	v_cvt_pk_bf16_f32 v52, v52, v53
	s_nop 0
	v_add_f32_e32 v58, 1.0, v58
	v_div_scale_f32 v64, s[6:7], v58, v58, v56
	v_rcp_f32_e32 v65, v64
	s_nop 0
	v_fma_f32 v67, -v64, v65, 1.0
	v_fmac_f32_e32 v65, v67, v65
	v_div_scale_f32 v67, vcc, v56, v58, v56
	v_mul_f32_e32 v69, v67, v65
	v_fma_f32 v70, -v64, v69, v67
	v_fmac_f32_e32 v69, v70, v65
	v_fma_f32 v64, -v64, v69, v67
	v_div_fmas_f32 v64, v64, v65, v69
	v_div_fixup_f32 v56, v64, v58, v56
	v_mul_f32_e32 v54, v54, v56
	v_and_b32_e32 v56, 0xffff0000, v57
	v_mul_f32_e32 v55, v55, v56
	v_and_b32_e32 v56, 0xffff0000, v59
	v_mul_f32_e32 v57, 0xbfb8aa3b, v56
	v_exp_f32_e32 v57, v57
	s_nop 0
	v_add_f32_e32 v57, 1.0, v57
	v_div_scale_f32 v58, s[6:7], v57, v57, v56
	v_rcp_f32_e32 v59, v58
	s_nop 0
	v_fma_f32 v64, -v58, v59, 1.0
	v_fmac_f32_e32 v59, v64, v59
	v_div_scale_f32 v64, vcc, v56, v57, v56
	v_mul_f32_e32 v65, v64, v59
	v_fma_f32 v66, -v58, v65, v64
	v_fmac_f32_e32 v65, v66, v59
	v_fma_f32 v58, -v58, v65, v64
	v_div_fmas_f32 v58, v58, v59, v65
	v_div_fixup_f32 v56, v58, v57, v56
	v_mul_f32_e32 v55, v55, v56
	v_cvt_pk_bf16_f32 v53, v54, v55
	v_lshl_add_u64 v[54:55], v[62:63], 0, v[60:61]
	v_mov_b32_e32 v106, v52
	v_mov_b32_e32 v107, v53
	global_store_dwordx4 v[54:55], v[104:107], off offset:-8
	v_or_b32_e32 v52, 32, v0
	v_mov_b32_e32 v53, v1
	v_lshlrev_b64 v[54:55], 11, v[52:53]
	v_lshl_add_u64 v[58:59], s[86:87], 0, v[54:55]
	v_lshl_add_u64 v[54:55], s[34:35], 0, v[54:55]
	v_lshl_add_u64 v[58:59], v[58:59], 0, v[2:3]
	v_lshl_add_u64 v[54:55], v[54:55], 0, v[2:3]
	v_lshlrev_b64 v[52:53], 12, v[52:53]
	v_lshl_add_u64 v[52:53], s[58:59], 0, v[52:53]
	v_lshl_add_u64 v[52:53], v[52:53], 0, s[10:11]
	s_waitcnt vmcnt(7)
	v_mov_b32_e32 v56, v180
	v_add_f32_e32 v48, v48, v56
	s_waitcnt vmcnt(6)
	v_mov_b32_e32 v62, v190
	v_mov_b32_e32 v63, v191
	v_lshlrev_b32_e32 v57, 16, v62
	v_mul_f32_e32 v48, v48, v57
	s_waitcnt vmcnt(5)
	v_mov_b32_e32 v64, v216
	v_mov_b32_e32 v65, v217
	v_lshlrev_b32_e32 v57, 16, v64
	v_mul_f32_e32 v66, 0xbfb8aa3b, v57
	v_exp_f32_e32 v66, v66
	v_add_f32_e32 v49, v49, v56
	v_add_f32_e32 v50, v50, v56
	v_add_f32_e32 v51, v51, v56
	v_add_f32_e32 v66, 1.0, v66
	v_div_scale_f32 v67, s[6:7], v66, v66, v57
	v_rcp_f32_e32 v69, v67
	v_add_f32_e32 v44, v44, v56
	v_add_f32_e32 v45, v45, v56
	v_add_f32_e32 v46, v46, v56
	v_fma_f32 v70, -v67, v69, 1.0
	v_fmac_f32_e32 v69, v70, v69
	v_div_scale_f32 v70, vcc, v57, v66, v57
	v_mul_f32_e32 v71, v70, v69
	v_fma_f32 v72, -v67, v71, v70
	v_fmac_f32_e32 v71, v72, v69
	v_fma_f32 v67, -v67, v71, v70
	v_div_fmas_f32 v67, v67, v69, v71
	v_div_fixup_f32 v57, v67, v66, v57
	v_mul_f32_e32 v48, v48, v57
	v_and_b32_e32 v57, 0xffff0000, v62
	v_mul_f32_e32 v49, v49, v57
	v_and_b32_e32 v57, 0xffff0000, v64
	v_mul_f32_e32 v62, 0xbfb8aa3b, v57
	v_exp_f32_e32 v62, v62
	v_add_f32_e32 v47, v47, v56
	v_add_f32_e32 v62, 1.0, v62
	v_div_scale_f32 v64, s[6:7], v62, v62, v57
	v_rcp_f32_e32 v66, v64
	s_nop 0
	v_fma_f32 v67, -v64, v66, 1.0
	v_fmac_f32_e32 v66, v67, v66
	v_div_scale_f32 v67, vcc, v57, v62, v57
	v_mul_f32_e32 v69, v67, v66
	v_fma_f32 v70, -v64, v69, v67
	v_fmac_f32_e32 v69, v70, v66
	v_fma_f32 v64, -v64, v69, v67
	v_div_fmas_f32 v64, v64, v66, v69
	v_div_fixup_f32 v57, v64, v62, v57
	v_mul_f32_e32 v49, v49, v57
	v_lshlrev_b32_e32 v57, 16, v63
	v_mul_f32_e32 v50, v50, v57
	v_lshlrev_b32_e32 v57, 16, v65
	v_mul_f32_e32 v62, 0xbfb8aa3b, v57
	v_exp_f32_e32 v62, v62
	v_cvt_pk_bf16_f32 v48, v48, v49
	s_nop 0
	v_add_f32_e32 v62, 1.0, v62
	v_div_scale_f32 v64, s[6:7], v62, v62, v57
	v_rcp_f32_e32 v66, v64
	s_nop 0
	v_fma_f32 v67, -v64, v66, 1.0
	v_fmac_f32_e32 v66, v67, v66
	v_div_scale_f32 v67, vcc, v57, v62, v57
	v_mul_f32_e32 v69, v67, v66
	v_fma_f32 v70, -v64, v69, v67
	v_fmac_f32_e32 v69, v70, v66
	v_fma_f32 v64, -v64, v69, v67
	v_div_fmas_f32 v64, v64, v66, v69
	v_div_fixup_f32 v57, v64, v62, v57
	v_mul_f32_e32 v50, v50, v57
	v_and_b32_e32 v57, 0xffff0000, v63
	v_mul_f32_e32 v51, v51, v57
	v_and_b32_e32 v57, 0xffff0000, v65
	v_mul_f32_e32 v62, 0xbfb8aa3b, v57
	v_exp_f32_e32 v62, v62
	s_nop 0
	v_add_f32_e32 v62, 1.0, v62
	v_div_scale_f32 v63, s[6:7], v62, v62, v57
	v_rcp_f32_e32 v64, v63
	s_nop 0
	v_fma_f32 v65, -v63, v64, 1.0
	v_fmac_f32_e32 v64, v65, v64
	v_div_scale_f32 v65, vcc, v57, v62, v57
	v_mul_f32_e32 v66, v65, v64
	v_fma_f32 v67, -v63, v66, v65
	v_fmac_f32_e32 v66, v67, v64
	v_fma_f32 v63, -v63, v66, v65
	v_div_fmas_f32 v63, v63, v64, v66
	v_div_fixup_f32 v57, v63, v62, v57
	v_mul_f32_e32 v51, v51, v57
	v_cvt_pk_bf16_f32 v49, v50, v51
	v_lshl_add_u64 v[50:51], v[52:53], 0, v[2:3]
	v_mov_b32_e32 v104, v48
	v_mov_b32_e32 v105, v49
	s_nop 0
	s_waitcnt vmcnt(6)
; __device__ __forceinline__ unsigned cvt_pk_bf16(float lo, float hi) { unsigned r; asm("v_cvt_pk_bf16_f32 %0, %1, %2" : "=v"(r) : "v"(lo), "v"(hi)); return r; }
; __device__ __forceinline__ float bflo(unsigned w) { return __uint_as_float(w << 16); }
; __device__ __forceinline__ float bfhi(unsigned w) { return __uint_as_float(w & 0xffff0000u); }
; __device__ __forceinline__ float silu(float x) { return x / (1.f + __expf(-x)); }
; __device__ __forceinline__ void gmlp_item(const Params& p, int l, int mc, int g, LAS unsigned char* lds) {
;     ...
;     const float* bsp = p.b_s + (size_t)(l * 4 + g) * 128;
; #pragma unroll
;     for (int tt = 0; tt < 8; ++tt) {
;         if (tt < ntt) {
;             const int tok = tok0 + tt * 16 + fr; const float bs = bsp[tt * 16 + fr];
; #pragma unroll
;             for (int ct = 0; ct < 2; ++ct) {
;                 const int cb = g * 256 + w * 32 + ct * 16 + fq * 4;
;                 const u32x2 uu = *(const u32x2*)((const u16*)(ws + WS_ZU) + (size_t)tok * 1024 + cb);
;                 const u32x2 gg = *(const u32x2*)((const u16*)(ws + WS_ZGB) + (size_t)tok * 1024 + cb);
;                 const float o0 = bflo(uu.x) * (acc[ct][tt][0] + bs) * silu(bflo(gg.x));
;                 const float o1 = bfhi(uu.x) * (acc[ct][tt][1] + bs) * silu(bfhi(gg.x));
;                 const float o2 = bflo(uu.y) * (acc[ct][tt][2] + bs) * silu(bflo(gg.y));
;                 const float o3 = bfhi(uu.y) * (acc[ct][tt][3] + bs) * silu(bfhi(gg.y));
;                 u32x2 wv; wv.x = cvt_pk_bf16(o0, o1); wv.y = cvt_pk_bf16(o2, o3);
;                 *(u32x2*)((u16*)(ws + WS_OBUF) + (size_t)tok * 2048 + 1024 + cb) = wv;
	v_mov_b32_e32 v48, v192
	v_mov_b32_e32 v49, v193
	v_lshlrev_b32_e32 v54, 16, v48
	v_mul_f32_e32 v44, v44, v54
	s_waitcnt vmcnt(5)
	v_mov_b32_e32 v50, v218
	v_mov_b32_e32 v51, v219
	v_lshlrev_b32_e32 v54, 16, v50
	v_mul_f32_e32 v55, 0xbfb8aa3b, v54
	v_exp_f32_e32 v55, v55
	v_and_b32_e32 v48, 0xffff0000, v48
	v_mul_f32_e32 v45, v45, v48
	v_and_b32_e32 v48, 0xffff0000, v50
	v_add_f32_e32 v55, 1.0, v55
	v_div_scale_f32 v57, s[6:7], v55, v55, v54
	v_rcp_f32_e32 v58, v57
	v_mul_f32_e32 v50, 0xbfb8aa3b, v48
	v_exp_f32_e32 v50, v50
	v_fma_f32 v59, -v57, v58, 1.0
	v_fmac_f32_e32 v58, v59, v58
	v_div_scale_f32 v59, vcc, v54, v55, v54
	v_mul_f32_e32 v62, v59, v58
	v_fma_f32 v63, -v57, v62, v59
	v_fmac_f32_e32 v62, v63, v58
	v_fma_f32 v57, -v57, v62, v59
	v_div_fmas_f32 v57, v57, v58, v62
	v_div_fixup_f32 v54, v57, v55, v54
	v_add_f32_e32 v50, 1.0, v50
	v_mul_f32_e32 v44, v44, v54
	v_div_scale_f32 v54, s[6:7], v50, v50, v48
	v_rcp_f32_e32 v55, v54
	s_nop 0
	v_fma_f32 v57, -v54, v55, 1.0
	v_fmac_f32_e32 v55, v57, v55
	v_div_scale_f32 v57, vcc, v48, v50, v48
	v_mul_f32_e32 v58, v57, v55
	v_fma_f32 v59, -v54, v58, v57
	v_fmac_f32_e32 v58, v59, v55
	v_fma_f32 v54, -v54, v58, v57
	v_div_fmas_f32 v54, v54, v55, v58
	v_div_fixup_f32 v48, v54, v50, v48
	v_mul_f32_e32 v45, v45, v48
	v_lshlrev_b32_e32 v48, 16, v49
	v_mul_f32_e32 v46, v46, v48
	v_lshlrev_b32_e32 v48, 16, v51
	v_mul_f32_e32 v50, 0xbfb8aa3b, v48
	v_exp_f32_e32 v50, v50
	v_cvt_pk_bf16_f32 v44, v44, v45
	s_nop 0
	v_add_f32_e32 v50, 1.0, v50
	v_div_scale_f32 v54, s[6:7], v50, v50, v48
	v_rcp_f32_e32 v55, v54
	s_nop 0
	v_fma_f32 v57, -v54, v55, 1.0
	v_fmac_f32_e32 v55, v57, v55
	v_div_scale_f32 v57, vcc, v48, v50, v48
	v_mul_f32_e32 v58, v57, v55
	v_fma_f32 v59, -v54, v58, v57
	v_fmac_f32_e32 v58, v59, v55
	v_fma_f32 v54, -v54, v58, v57
	v_div_fmas_f32 v54, v54, v55, v58
	v_div_fixup_f32 v48, v54, v50, v48
	v_mul_f32_e32 v46, v46, v48
	v_and_b32_e32 v48, 0xffff0000, v49
	v_mul_f32_e32 v47, v47, v48
	v_and_b32_e32 v48, 0xffff0000, v51
	v_mul_f32_e32 v49, 0xbfb8aa3b, v48
	v_exp_f32_e32 v49, v49
	s_nop 0
	v_add_f32_e32 v49, 1.0, v49
	v_div_scale_f32 v50, s[6:7], v49, v49, v48
	v_rcp_f32_e32 v51, v50
	s_nop 0
	v_fma_f32 v54, -v50, v51, 1.0
	v_fmac_f32_e32 v51, v54, v51
	v_div_scale_f32 v54, vcc, v48, v49, v48
	v_mul_f32_e32 v55, v54, v51
	v_fma_f32 v56, -v50, v55, v54
	v_fmac_f32_e32 v55, v56, v51
	v_fma_f32 v50, -v50, v55, v54
	v_div_fmas_f32 v50, v50, v51, v55
	v_div_fixup_f32 v48, v50, v49, v48
	v_mul_f32_e32 v47, v47, v48
	v_cvt_pk_bf16_f32 v45, v46, v47
	v_lshl_add_u64 v[46:47], v[52:53], 0, v[60:61]
	v_mov_b32_e32 v106, v44
	v_mov_b32_e32 v107, v45
	global_store_dwordx4 v[46:47], v[104:107], off offset:-8
	v_or_b32_e32 v44, 48, v0
	v_mov_b32_e32 v45, v1
	v_lshlrev_b64 v[46:47], 11, v[44:45]
	v_lshl_add_u64 v[50:51], s[86:87], 0, v[46:47]
	v_lshl_add_u64 v[46:47], s[34:35], 0, v[46:47]
	v_lshl_add_u64 v[50:51], v[50:51], 0, v[2:3]
	v_lshl_add_u64 v[46:47], v[46:47], 0, v[2:3]
	v_lshlrev_b64 v[44:45], 12, v[44:45]
	v_lshl_add_u64 v[44:45], s[58:59], 0, v[44:45]
	v_lshl_add_u64 v[44:45], v[44:45], 0, s[10:11]
	s_waitcnt vmcnt(5)
	v_mov_b32_e32 v48, v181
	v_add_f32_e32 v40, v40, v48
	s_waitcnt vmcnt(4)
	v_mov_b32_e32 v52, v194
	v_mov_b32_e32 v53, v195
	v_lshlrev_b32_e32 v49, 16, v52
	v_mul_f32_e32 v40, v40, v49
	s_waitcnt vmcnt(3)
	v_mov_b32_e32 v54, v220
	v_mov_b32_e32 v55, v221
	v_lshlrev_b32_e32 v49, 16, v54
	v_mul_f32_e32 v56, 0xbfb8aa3b, v49
	v_exp_f32_e32 v56, v56
	v_add_f32_e32 v41, v41, v48
	v_add_f32_e32 v42, v42, v48
	v_add_f32_e32 v43, v43, v48
	v_add_f32_e32 v56, 1.0, v56
	v_div_scale_f32 v57, s[6:7], v56, v56, v49
	v_rcp_f32_e32 v58, v57
	v_add_f32_e32 v36, v36, v48
	v_add_f32_e32 v37, v37, v48
	v_add_f32_e32 v38, v38, v48
	v_fma_f32 v59, -v57, v58, 1.0
	v_fmac_f32_e32 v58, v59, v58
	v_div_scale_f32 v59, vcc, v49, v56, v49
	v_mul_f32_e32 v62, v59, v58
	v_fma_f32 v63, -v57, v62, v59
	v_fmac_f32_e32 v62, v63, v58
	v_fma_f32 v57, -v57, v62, v59
	v_div_fmas_f32 v57, v57, v58, v62
	v_div_fixup_f32 v49, v57, v56, v49
	v_mul_f32_e32 v40, v40, v49
	v_and_b32_e32 v49, 0xffff0000, v52
	v_mul_f32_e32 v41, v41, v49
	v_and_b32_e32 v49, 0xffff0000, v54
	v_mul_f32_e32 v52, 0xbfb8aa3b, v49
	v_exp_f32_e32 v52, v52
	v_add_f32_e32 v39, v39, v48
	v_add_f32_e32 v52, 1.0, v52
	v_div_scale_f32 v54, s[6:7], v52, v52, v49
	v_rcp_f32_e32 v56, v54
	s_nop 0
	v_fma_f32 v57, -v54, v56, 1.0
	v_fmac_f32_e32 v56, v57, v56
	v_div_scale_f32 v57, vcc, v49, v52, v49
	v_mul_f32_e32 v58, v57, v56
	v_fma_f32 v59, -v54, v58, v57
	v_fmac_f32_e32 v58, v59, v56
	v_fma_f32 v54, -v54, v58, v57
	v_div_fmas_f32 v54, v54, v56, v58
	v_div_fixup_f32 v49, v54, v52, v49
	v_mul_f32_e32 v41, v41, v49
	v_lshlrev_b32_e32 v49, 16, v53
	v_mul_f32_e32 v42, v42, v49
	v_lshlrev_b32_e32 v49, 16, v55
	v_mul_f32_e32 v52, 0xbfb8aa3b, v49
	v_exp_f32_e32 v52, v52
	v_cvt_pk_bf16_f32 v40, v40, v41
	s_nop 0
	v_add_f32_e32 v52, 1.0, v52
	v_div_scale_f32 v54, s[6:7], v52, v52, v49
	v_rcp_f32_e32 v56, v54
	s_nop 0
	v_fma_f32 v57, -v54, v56, 1.0
	v_fmac_f32_e32 v56, v57, v56
	v_div_scale_f32 v57, vcc, v49, v52, v49
	v_mul_f32_e32 v58, v57, v56
	v_fma_f32 v59, -v54, v58, v57
	v_fmac_f32_e32 v58, v59, v56
	v_fma_f32 v54, -v54, v58, v57
	v_div_fmas_f32 v54, v54, v56, v58
	v_div_fixup_f32 v49, v54, v52, v49
	v_mul_f32_e32 v42, v42, v49
	v_and_b32_e32 v49, 0xffff0000, v53
	v_mul_f32_e32 v43, v43, v49
	v_and_b32_e32 v49, 0xffff0000, v55
	v_mul_f32_e32 v52, 0xbfb8aa3b, v49
	v_exp_f32_e32 v52, v52
	s_nop 0
	v_add_f32_e32 v52, 1.0, v52
	v_div_scale_f32 v53, s[6:7], v52, v52, v49
	v_rcp_f32_e32 v54, v53
	s_nop 0
	v_fma_f32 v55, -v53, v54, 1.0
	v_fmac_f32_e32 v54, v55, v54
	v_div_scale_f32 v55, vcc, v49, v52, v49
	v_mul_f32_e32 v56, v55, v54
	v_fma_f32 v57, -v53, v56, v55
	v_fmac_f32_e32 v56, v57, v54
	v_fma_f32 v53, -v53, v56, v55
	v_div_fmas_f32 v53, v53, v54, v56
	v_div_fixup_f32 v49, v53, v52, v49
	v_mul_f32_e32 v43, v43, v49
	v_cvt_pk_bf16_f32 v41, v42, v43
	v_lshl_add_u64 v[42:43], v[44:45], 0, v[2:3]
	v_mov_b32_e32 v104, v40
	v_mov_b32_e32 v105, v41
	s_nop 0
	s_waitcnt vmcnt(4)
; __device__ __forceinline__ unsigned cvt_pk_bf16(float lo, float hi) { unsigned r; asm("v_cvt_pk_bf16_f32 %0, %1, %2" : "=v"(r) : "v"(lo), "v"(hi)); return r; }
; __device__ __forceinline__ float bflo(unsigned w) { return __uint_as_float(w << 16); }
; __device__ __forceinline__ float bfhi(unsigned w) { return __uint_as_float(w & 0xffff0000u); }
; __device__ __forceinline__ float silu(float x) { return x / (1.f + __expf(-x)); }
; __device__ __forceinline__ void gmlp_item(const Params& p, int l, int mc, int g, LAS unsigned char* lds) {
;     ...
;     const float* bsp = p.b_s + (size_t)(l * 4 + g) * 128;
; #pragma unroll
;     for (int tt = 0; tt < 8; ++tt) {
;         if (tt < ntt) {
;             const int tok = tok0 + tt * 16 + fr; const float bs = bsp[tt * 16 + fr];
; #pragma unroll
;             for (int ct = 0; ct < 2; ++ct) {
;                 const int cb = g * 256 + w * 32 + ct * 16 + fq * 4;
;                 const u32x2 uu = *(const u32x2*)((const u16*)(ws + WS_ZU) + (size_t)tok * 1024 + cb);
;                 const u32x2 gg = *(const u32x2*)((const u16*)(ws + WS_ZGB) + (size_t)tok * 1024 + cb);
;                 const float o0 = bflo(uu.x) * (acc[ct][tt][0] + bs) * silu(bflo(gg.x));
;                 const float o1 = bfhi(uu.x) * (acc[ct][tt][1] + bs) * silu(bfhi(gg.x));
;                 const float o2 = bflo(uu.y) * (acc[ct][tt][2] + bs) * silu(bflo(gg.y));
;                 const float o3 = bfhi(uu.y) * (acc[ct][tt][3] + bs) * silu(bfhi(gg.y));
;                 u32x2 wv; wv.x = cvt_pk_bf16(o0, o1); wv.y = cvt_pk_bf16(o2, o3);
;                 *(u32x2*)((u16*)(ws + WS_OBUF) + (size_t)tok * 2048 + 1024 + cb) = wv;
	v_mov_b32_e32 v40, v196
	v_mov_b32_e32 v41, v197
	v_lshlrev_b32_e32 v46, 16, v40
	v_mul_f32_e32 v36, v36, v46
	s_waitcnt vmcnt(3)
	v_mov_b32_e32 v42, v222
	v_mov_b32_e32 v43, v223
	v_lshlrev_b32_e32 v46, 16, v42
	v_mul_f32_e32 v47, 0xbfb8aa3b, v46
	v_exp_f32_e32 v47, v47
	v_and_b32_e32 v40, 0xffff0000, v40
	v_mul_f32_e32 v37, v37, v40
	v_and_b32_e32 v40, 0xffff0000, v42
	v_add_f32_e32 v47, 1.0, v47
	v_div_scale_f32 v49, s[6:7], v47, v47, v46
	v_rcp_f32_e32 v50, v49
	v_mul_f32_e32 v42, 0xbfb8aa3b, v40
	v_exp_f32_e32 v42, v42
	v_fma_f32 v51, -v49, v50, 1.0
	v_fmac_f32_e32 v50, v51, v50
	v_div_scale_f32 v51, vcc, v46, v47, v46
	v_mul_f32_e32 v52, v51, v50
	v_fma_f32 v53, -v49, v52, v51
	v_fmac_f32_e32 v52, v53, v50
	v_fma_f32 v49, -v49, v52, v51
	v_div_fmas_f32 v49, v49, v50, v52
	v_div_fixup_f32 v46, v49, v47, v46
	v_add_f32_e32 v42, 1.0, v42
	v_mul_f32_e32 v36, v36, v46
	v_div_scale_f32 v46, s[6:7], v42, v42, v40
	v_rcp_f32_e32 v47, v46
	s_nop 0
	v_fma_f32 v49, -v46, v47, 1.0
	v_fmac_f32_e32 v47, v49, v47
	v_div_scale_f32 v49, vcc, v40, v42, v40
	v_mul_f32_e32 v50, v49, v47
	v_fma_f32 v51, -v46, v50, v49
	v_fmac_f32_e32 v50, v51, v47
	v_fma_f32 v46, -v46, v50, v49
	v_div_fmas_f32 v46, v46, v47, v50
	v_div_fixup_f32 v40, v46, v42, v40
	v_mul_f32_e32 v37, v37, v40
	v_lshlrev_b32_e32 v40, 16, v41
	v_mul_f32_e32 v38, v38, v40
	v_lshlrev_b32_e32 v40, 16, v43
	v_mul_f32_e32 v42, 0xbfb8aa3b, v40
	v_exp_f32_e32 v42, v42
	v_cvt_pk_bf16_f32 v36, v36, v37
	s_nop 0
	v_add_f32_e32 v42, 1.0, v42
	v_div_scale_f32 v46, s[6:7], v42, v42, v40
	v_rcp_f32_e32 v47, v46
	s_nop 0
	v_fma_f32 v49, -v46, v47, 1.0
	v_fmac_f32_e32 v47, v49, v47
	v_div_scale_f32 v49, vcc, v40, v42, v40
	v_mul_f32_e32 v50, v49, v47
	v_fma_f32 v51, -v46, v50, v49
	v_fmac_f32_e32 v50, v51, v47
	v_fma_f32 v46, -v46, v50, v49
	v_div_fmas_f32 v46, v46, v47, v50
	v_div_fixup_f32 v40, v46, v42, v40
	v_mul_f32_e32 v38, v38, v40
	v_and_b32_e32 v40, 0xffff0000, v41
	v_mul_f32_e32 v39, v39, v40
	v_and_b32_e32 v40, 0xffff0000, v43
	v_mul_f32_e32 v41, 0xbfb8aa3b, v40
	v_exp_f32_e32 v41, v41
	s_nop 0
	v_add_f32_e32 v41, 1.0, v41
	v_div_scale_f32 v42, s[6:7], v41, v41, v40
	v_rcp_f32_e32 v43, v42
	s_nop 0
	v_fma_f32 v46, -v42, v43, 1.0
	v_fmac_f32_e32 v43, v46, v43
	v_div_scale_f32 v46, vcc, v40, v41, v40
	v_mul_f32_e32 v47, v46, v43
	v_fma_f32 v48, -v42, v47, v46
	v_fmac_f32_e32 v47, v48, v43
	v_fma_f32 v42, -v42, v47, v46
	v_div_fmas_f32 v42, v42, v43, v47
	v_div_fixup_f32 v40, v42, v41, v40
	v_mul_f32_e32 v39, v39, v40
	v_cvt_pk_bf16_f32 v37, v38, v39
	v_lshl_add_u64 v[38:39], v[44:45], 0, v[60:61]
	s_and_b64 vcc, exec, s[38:39]
	v_mov_b32_e32 v106, v36
	v_mov_b32_e32 v107, v37
	global_store_dwordx4 v[38:39], v[104:107], off offset:-8
	s_cbranch_vccnz .LBB0_768
	s_mov_b64 s[98:99], 0x8000
	v_mov_b32_e32 v224, v228
	v_mov_b32_e32 v225, v229
	v_mov_b32_e32 v226, v230
	v_mov_b32_e32 v227, v231
	global_load_dword v178, v[232:233], off
	global_load_dwordx4 v[182:185], v[224:225], off
	global_load_dwordx4 v[208:211], v[226:227], off
	v_lshl_add_u64 v[224:225], v[224:225], 0, s[98:99]
	v_lshl_add_u64 v[226:227], v[226:227], 0, s[98:99]
	global_load_dword v179, v[232:233], off offset:64
	global_load_dwordx4 v[186:189], v[224:225], off
	global_load_dwordx4 v[212:215], v[226:227], off
	v_lshl_add_u64 v[224:225], v[224:225], 0, s[98:99]
	v_lshl_add_u64 v[226:227], v[226:227], 0, s[98:99]
	global_load_dword v180, v[232:233], off offset:128
	global_load_dwordx4 v[190:193], v[224:225], off
	global_load_dwordx4 v[216:219], v[226:227], off
	v_lshl_add_u64 v[224:225], v[224:225], 0, s[98:99]
	v_lshl_add_u64 v[226:227], v[226:227], 0, s[98:99]
	global_load_dword v181, v[232:233], off offset:192
	global_load_dwordx4 v[194:197], v[224:225], off
	global_load_dwordx4 v[220:223], v[226:227], off
	v_lshl_add_u64 v[224:225], v[224:225], 0, s[98:99]
	v_lshl_add_u64 v[226:227], v[226:227], 0, s[98:99]
	v_add_u32_e32 v38, 64, v0
	v_mov_b32_e32 v39, v1
	v_lshlrev_b64 v[40:41], 11, v[38:39]
	v_mov_b32_e32 v69, v1
	v_lshl_add_u64 v[44:45], s[86:87], 0, v[40:41]
	v_lshl_add_u64 v[36:37], s[0:1], 0, v[68:69]
	v_lshl_add_u64 v[40:41], s[34:35], 0, v[40:41]
	v_lshl_add_u64 v[44:45], v[44:45], 0, v[2:3]
	v_lshl_add_u64 v[40:41], v[40:41], 0, v[2:3]
	v_lshlrev_b64 v[38:39], 12, v[38:39]
	v_lshl_add_u64 v[38:39], s[58:59], 0, v[38:39]
	s_mov_b64 s[6:7], 0x2958c800
	v_lshl_add_u64 v[38:39], v[38:39], 0, s[6:7]
	s_waitcnt vmcnt(11)
	v_mov_b32_e32 v42, v178
	v_add_f32_e32 v32, v32, v42
	s_waitcnt vmcnt(10)
	v_mov_b32_e32 v46, v182
	v_mov_b32_e32 v47, v183
	v_lshlrev_b32_e32 v43, 16, v46
	v_mul_f32_e32 v32, v32, v43
	s_waitcnt vmcnt(9)
; __device__ __forceinline__ unsigned cvt_pk_bf16(float lo, float hi) { unsigned r; asm("v_cvt_pk_bf16_f32 %0, %1, %2" : "=v"(r) : "v"(lo), "v"(hi)); return r; }
; __device__ __forceinline__ float bflo(unsigned w) { return __uint_as_float(w << 16); }
; __device__ __forceinline__ float bfhi(unsigned w) { return __uint_as_float(w & 0xffff0000u); }
; __device__ __forceinline__ float silu(float x) { return x / (1.f + __expf(-x)); }
; __device__ __forceinline__ void gmlp_item(const Params& p, int l, int mc, int g, LAS unsigned char* lds) {
;     ...
;     const float* bsp = p.b_s + (size_t)(l * 4 + g) * 128;
; #pragma unroll
;     for (int tt = 0; tt < 8; ++tt) {
;         if (tt < ntt) {
;             const int tok = tok0 + tt * 16 + fr; const float bs = bsp[tt * 16 + fr];
; #pragma unroll
;             for (int ct = 0; ct < 2; ++ct) {
;                 const int cb = g * 256 + w * 32 + ct * 16 + fq * 4;
;                 const u32x2 uu = *(const u32x2*)((const u16*)(ws + WS_ZU) + (size_t)tok * 1024 + cb);
;                 const u32x2 gg = *(const u32x2*)((const u16*)(ws + WS_ZGB) + (size_t)tok * 1024 + cb);
;                 const float o0 = bflo(uu.x) * (acc[ct][tt][0] + bs) * silu(bflo(gg.x));
;                 const float o1 = bfhi(uu.x) * (acc[ct][tt][1] + bs) * silu(bfhi(gg.x));
;                 const float o2 = bflo(uu.y) * (acc[ct][tt][2] + bs) * silu(bflo(gg.y));
;                 const float o3 = bfhi(uu.y) * (acc[ct][tt][3] + bs) * silu(bfhi(gg.y));
;                 u32x2 wv; wv.x = cvt_pk_bf16(o0, o1); wv.y = cvt_pk_bf16(o2, o3);
;                 *(u32x2*)((u16*)(ws + WS_OBUF) + (size_t)tok * 2048 + 1024 + cb) = wv;
	v_mov_b32_e32 v48, v208
	v_mov_b32_e32 v49, v209
	v_lshlrev_b32_e32 v43, 16, v48
	v_mul_f32_e32 v50, 0xbfb8aa3b, v43
	v_exp_f32_e32 v50, v50
	v_add_f32_e32 v33, v33, v42
	v_add_f32_e32 v34, v34, v42
	v_add_f32_e32 v35, v35, v42
	v_add_f32_e32 v50, 1.0, v50
	v_div_scale_f32 v51, s[0:1], v50, v50, v43
	v_rcp_f32_e32 v52, v51
	v_add_f32_e32 v28, v28, v42
	v_add_f32_e32 v29, v29, v42
	v_add_f32_e32 v30, v30, v42
	v_fma_f32 v53, -v51, v52, 1.0
	v_fmac_f32_e32 v52, v53, v52
	v_div_scale_f32 v53, vcc, v43, v50, v43
	v_mul_f32_e32 v54, v53, v52
	v_fma_f32 v55, -v51, v54, v53
	v_fmac_f32_e32 v54, v55, v52
	v_fma_f32 v51, -v51, v54, v53
	v_div_fmas_f32 v51, v51, v52, v54
	v_div_fixup_f32 v43, v51, v50, v43
	v_mul_f32_e32 v32, v32, v43
	v_and_b32_e32 v43, 0xffff0000, v46
	v_mul_f32_e32 v33, v33, v43
	v_and_b32_e32 v43, 0xffff0000, v48
	v_mul_f32_e32 v46, 0xbfb8aa3b, v43
	v_exp_f32_e32 v46, v46
	v_add_f32_e32 v31, v31, v42
	v_add_f32_e32 v46, 1.0, v46
	v_div_scale_f32 v48, s[0:1], v46, v46, v43
	v_rcp_f32_e32 v50, v48
	s_nop 0
	v_fma_f32 v51, -v48, v50, 1.0
	v_fmac_f32_e32 v50, v51, v50
	v_div_scale_f32 v51, vcc, v43, v46, v43
	v_mul_f32_e32 v52, v51, v50
	v_fma_f32 v53, -v48, v52, v51
	v_fmac_f32_e32 v52, v53, v50
	v_fma_f32 v48, -v48, v52, v51
	v_div_fmas_f32 v48, v48, v50, v52
	v_div_fixup_f32 v43, v48, v46, v43
	v_mul_f32_e32 v33, v33, v43
	v_lshlrev_b32_e32 v43, 16, v47
	v_mul_f32_e32 v34, v34, v43
	v_lshlrev_b32_e32 v43, 16, v49
	v_mul_f32_e32 v46, 0xbfb8aa3b, v43
	v_exp_f32_e32 v46, v46
	v_cvt_pk_bf16_f32 v32, v32, v33
	s_nop 0
	v_add_f32_e32 v46, 1.0, v46
	v_div_scale_f32 v48, s[0:1], v46, v46, v43
	v_rcp_f32_e32 v50, v48
	s_nop 0
	v_fma_f32 v51, -v48, v50, 1.0
	v_fmac_f32_e32 v50, v51, v50
	v_div_scale_f32 v51, vcc, v43, v46, v43
	v_mul_f32_e32 v52, v51, v50
	v_fma_f32 v53, -v48, v52, v51
	v_fmac_f32_e32 v52, v53, v50
	v_fma_f32 v48, -v48, v52, v51
	v_div_fmas_f32 v48, v48, v50, v52
	v_div_fixup_f32 v43, v48, v46, v43
	v_mul_f32_e32 v34, v34, v43
	v_and_b32_e32 v43, 0xffff0000, v47
	v_mul_f32_e32 v35, v35, v43
	v_and_b32_e32 v43, 0xffff0000, v49
	v_mul_f32_e32 v46, 0xbfb8aa3b, v43
	v_exp_f32_e32 v46, v46
	s_nop 0
	v_add_f32_e32 v46, 1.0, v46
	v_div_scale_f32 v47, s[0:1], v46, v46, v43
	v_rcp_f32_e32 v48, v47
	s_nop 0
	v_fma_f32 v49, -v47, v48, 1.0
	v_fmac_f32_e32 v48, v49, v48
	v_div_scale_f32 v49, vcc, v43, v46, v43
	v_mul_f32_e32 v50, v49, v48
	v_fma_f32 v51, -v47, v50, v49
	v_fmac_f32_e32 v50, v51, v48
	v_fma_f32 v47, -v47, v50, v49
	v_div_fmas_f32 v47, v47, v48, v50
	v_div_fixup_f32 v43, v47, v46, v43
	v_mul_f32_e32 v35, v35, v43
	v_cvt_pk_bf16_f32 v33, v34, v35
	v_lshl_add_u64 v[34:35], v[38:39], 0, v[2:3]
	v_mov_b32_e32 v104, v32
	v_mov_b32_e32 v105, v33
	s_nop 0
	s_waitcnt vmcnt(10)
	v_mov_b32_e32 v32, v184
	v_mov_b32_e32 v33, v185
	v_lshlrev_b32_e32 v40, 16, v32
	v_mul_f32_e32 v28, v28, v40
	s_waitcnt vmcnt(9)
	v_mov_b32_e32 v34, v210
	v_mov_b32_e32 v35, v211
	v_lshlrev_b32_e32 v40, 16, v34
	v_mul_f32_e32 v41, 0xbfb8aa3b, v40
	v_exp_f32_e32 v41, v41
	v_and_b32_e32 v32, 0xffff0000, v32
	v_mul_f32_e32 v29, v29, v32
	v_and_b32_e32 v32, 0xffff0000, v34
	v_add_f32_e32 v41, 1.0, v41
	v_div_scale_f32 v43, s[0:1], v41, v41, v40
	v_rcp_f32_e32 v44, v43
	v_mul_f32_e32 v34, 0xbfb8aa3b, v32
	v_exp_f32_e32 v34, v34
	v_fma_f32 v45, -v43, v44, 1.0
	v_fmac_f32_e32 v44, v45, v44
	v_div_scale_f32 v45, vcc, v40, v41, v40
	v_mul_f32_e32 v46, v45, v44
	v_fma_f32 v47, -v43, v46, v45
	v_fmac_f32_e32 v46, v47, v44
	v_fma_f32 v43, -v43, v46, v45
	v_div_fmas_f32 v43, v43, v44, v46
	v_div_fixup_f32 v40, v43, v41, v40
	v_add_f32_e32 v34, 1.0, v34
	v_mul_f32_e32 v28, v28, v40
	v_div_scale_f32 v40, s[0:1], v34, v34, v32
	v_rcp_f32_e32 v41, v40
	s_nop 0
	v_fma_f32 v43, -v40, v41, 1.0
	v_fmac_f32_e32 v41, v43, v41
	v_div_scale_f32 v43, vcc, v32, v34, v32
	v_mul_f32_e32 v44, v43, v41
	v_fma_f32 v45, -v40, v44, v43
	v_fmac_f32_e32 v44, v45, v41
	v_fma_f32 v40, -v40, v44, v43
	v_div_fmas_f32 v40, v40, v41, v44
	v_div_fixup_f32 v32, v40, v34, v32
	v_mul_f32_e32 v29, v29, v32
	v_lshlrev_b32_e32 v32, 16, v33
	v_mul_f32_e32 v30, v30, v32
	v_lshlrev_b32_e32 v32, 16, v35
	v_mul_f32_e32 v34, 0xbfb8aa3b, v32
	v_exp_f32_e32 v34, v34
	v_cvt_pk_bf16_f32 v28, v28, v29
	s_nop 0
	v_add_f32_e32 v34, 1.0, v34
	v_div_scale_f32 v40, s[0:1], v34, v34, v32
	v_rcp_f32_e32 v41, v40
	s_nop 0
	v_fma_f32 v43, -v40, v41, 1.0
	v_fmac_f32_e32 v41, v43, v41
	v_div_scale_f32 v43, vcc, v32, v34, v32
	v_mul_f32_e32 v44, v43, v41
	v_fma_f32 v45, -v40, v44, v43
	v_fmac_f32_e32 v44, v45, v41
	v_fma_f32 v40, -v40, v44, v43
	v_div_fmas_f32 v40, v40, v41, v44
	v_div_fixup_f32 v32, v40, v34, v32
	v_mul_f32_e32 v30, v30, v32
	v_and_b32_e32 v32, 0xffff0000, v33
	v_mul_f32_e32 v31, v31, v32
	v_and_b32_e32 v32, 0xffff0000, v35
	v_mul_f32_e32 v33, 0xbfb8aa3b, v32
	v_exp_f32_e32 v33, v33
	s_nop 0
	v_add_f32_e32 v33, 1.0, v33
	v_div_scale_f32 v34, s[0:1], v33, v33, v32
	v_rcp_f32_e32 v35, v34
	s_nop 0
	v_fma_f32 v40, -v34, v35, 1.0
	v_fmac_f32_e32 v35, v40, v35
	v_div_scale_f32 v40, vcc, v32, v33, v32
	v_mul_f32_e32 v41, v40, v35
	v_fma_f32 v42, -v34, v41, v40
	v_fmac_f32_e32 v41, v42, v35
	v_fma_f32 v34, -v34, v41, v40
	v_div_fmas_f32 v34, v34, v35, v41
	v_div_fixup_f32 v32, v34, v33, v32
	v_mul_f32_e32 v31, v31, v32
	v_cvt_pk_bf16_f32 v29, v30, v31
	v_lshl_add_u64 v[30:31], v[38:39], 0, v[60:61]
	v_mov_b32_e32 v106, v28
	v_mov_b32_e32 v107, v29
	global_store_dwordx4 v[30:31], v[104:107], off offset:-8
	v_add_u32_e32 v28, 0x50, v0
	v_mov_b32_e32 v29, v1
	v_lshlrev_b64 v[30:31], 11, v[28:29]
	v_lshl_add_u64 v[34:35], s[86:87], 0, v[30:31]
	v_lshl_add_u64 v[30:31], s[34:35], 0, v[30:31]
	v_lshl_add_u64 v[34:35], v[34:35], 0, v[2:3]
	v_lshl_add_u64 v[30:31], v[30:31], 0, v[2:3]
	v_lshlrev_b64 v[28:29], 12, v[28:29]
	v_lshl_add_u64 v[28:29], s[58:59], 0, v[28:29]
	v_lshl_add_u64 v[28:29], v[28:29], 0, s[6:7]
	s_waitcnt vmcnt(9)
; __device__ __forceinline__ unsigned cvt_pk_bf16(float lo, float hi) { unsigned r; asm("v_cvt_pk_bf16_f32 %0, %1, %2" : "=v"(r) : "v"(lo), "v"(hi)); return r; }
; __device__ __forceinline__ float bflo(unsigned w) { return __uint_as_float(w << 16); }
; __device__ __forceinline__ float bfhi(unsigned w) { return __uint_as_float(w & 0xffff0000u); }
; __device__ __forceinline__ float silu(float x) { return x / (1.f + __expf(-x)); }
; __device__ __forceinline__ void gmlp_item(const Params& p, int l, int mc, int g, LAS unsigned char* lds) {
;     ...
;     const float* bsp = p.b_s + (size_t)(l * 4 + g) * 128;
; #pragma unroll
;     for (int tt = 0; tt < 8; ++tt) {
;         if (tt < ntt) {
;             const int tok = tok0 + tt * 16 + fr; const float bs = bsp[tt * 16 + fr];
; #pragma unroll
;             for (int ct = 0; ct < 2; ++ct) {
;                 const int cb = g * 256 + w * 32 + ct * 16 + fq * 4;
;                 const u32x2 uu = *(const u32x2*)((const u16*)(ws + WS_ZU) + (size_t)tok * 1024 + cb);
;                 const u32x2 gg = *(const u32x2*)((const u16*)(ws + WS_ZGB) + (size_t)tok * 1024 + cb);
;                 const float o0 = bflo(uu.x) * (acc[ct][tt][0] + bs) * silu(bflo(gg.x));
;                 const float o1 = bfhi(uu.x) * (acc[ct][tt][1] + bs) * silu(bfhi(gg.x));
;                 const float o2 = bflo(uu.y) * (acc[ct][tt][2] + bs) * silu(bflo(gg.y));
;                 const float o3 = bfhi(uu.y) * (acc[ct][tt][3] + bs) * silu(bfhi(gg.y));
;                 u32x2 wv; wv.x = cvt_pk_bf16(o0, o1); wv.y = cvt_pk_bf16(o2, o3);
;                 *(u32x2*)((u16*)(ws + WS_OBUF) + (size_t)tok * 2048 + 1024 + cb) = wv;
	v_mov_b32_e32 v32, v179
	v_add_f32_e32 v24, v24, v32
	s_waitcnt vmcnt(8)
	v_mov_b32_e32 v38, v186
	v_mov_b32_e32 v39, v187
	v_lshlrev_b32_e32 v33, 16, v38
	v_mul_f32_e32 v24, v24, v33
	s_waitcnt vmcnt(7)
	v_mov_b32_e32 v40, v212
	v_mov_b32_e32 v41, v213
	v_lshlrev_b32_e32 v33, 16, v40
	v_mul_f32_e32 v42, 0xbfb8aa3b, v33
	v_exp_f32_e32 v42, v42
	v_add_f32_e32 v25, v25, v32
	v_add_f32_e32 v26, v26, v32
	v_add_f32_e32 v27, v27, v32
	v_add_f32_e32 v42, 1.0, v42
	v_div_scale_f32 v43, s[0:1], v42, v42, v33
	v_rcp_f32_e32 v44, v43
	v_add_f32_e32 v20, v20, v32
	v_add_f32_e32 v21, v21, v32
	v_add_f32_e32 v22, v22, v32
	v_fma_f32 v45, -v43, v44, 1.0
	v_fmac_f32_e32 v44, v45, v44
	v_div_scale_f32 v45, vcc, v33, v42, v33
	v_mul_f32_e32 v46, v45, v44
	v_fma_f32 v47, -v43, v46, v45
	v_fmac_f32_e32 v46, v47, v44
	v_fma_f32 v43, -v43, v46, v45
	v_div_fmas_f32 v43, v43, v44, v46
	v_div_fixup_f32 v33, v43, v42, v33
	v_mul_f32_e32 v24, v24, v33
	v_and_b32_e32 v33, 0xffff0000, v38
	v_mul_f32_e32 v25, v25, v33
	v_and_b32_e32 v33, 0xffff0000, v40
	v_mul_f32_e32 v38, 0xbfb8aa3b, v33
	v_exp_f32_e32 v38, v38
	v_add_f32_e32 v23, v23, v32
	v_add_f32_e32 v38, 1.0, v38
	v_div_scale_f32 v40, s[0:1], v38, v38, v33
	v_rcp_f32_e32 v42, v40
	s_nop 0
	v_fma_f32 v43, -v40, v42, 1.0
	v_fmac_f32_e32 v42, v43, v42
	v_div_scale_f32 v43, vcc, v33, v38, v33
	v_mul_f32_e32 v44, v43, v42
	v_fma_f32 v45, -v40, v44, v43
	v_fmac_f32_e32 v44, v45, v42
	v_fma_f32 v40, -v40, v44, v43
	v_div_fmas_f32 v40, v40, v42, v44
	v_div_fixup_f32 v33, v40, v38, v33
	v_mul_f32_e32 v25, v25, v33
	v_lshlrev_b32_e32 v33, 16, v39
	v_mul_f32_e32 v26, v26, v33
	v_lshlrev_b32_e32 v33, 16, v41
	v_mul_f32_e32 v38, 0xbfb8aa3b, v33
	v_exp_f32_e32 v38, v38
	v_cvt_pk_bf16_f32 v24, v24, v25
	s_nop 0
	v_add_f32_e32 v38, 1.0, v38
	v_div_scale_f32 v40, s[0:1], v38, v38, v33
	v_rcp_f32_e32 v42, v40
	s_nop 0
	v_fma_f32 v43, -v40, v42, 1.0
	v_fmac_f32_e32 v42, v43, v42
	v_div_scale_f32 v43, vcc, v33, v38, v33
	v_mul_f32_e32 v44, v43, v42
	v_fma_f32 v45, -v40, v44, v43
	v_fmac_f32_e32 v44, v45, v42
	v_fma_f32 v40, -v40, v44, v43
	v_div_fmas_f32 v40, v40, v42, v44
	v_div_fixup_f32 v33, v40, v38, v33
	v_mul_f32_e32 v26, v26, v33
	v_and_b32_e32 v33, 0xffff0000, v39
	v_mul_f32_e32 v27, v27, v33
	v_and_b32_e32 v33, 0xffff0000, v41
	v_mul_f32_e32 v38, 0xbfb8aa3b, v33
	v_exp_f32_e32 v38, v38
	s_nop 0
	v_add_f32_e32 v38, 1.0, v38
	v_div_scale_f32 v39, s[0:1], v38, v38, v33
	v_rcp_f32_e32 v40, v39
	s_nop 0
	v_fma_f32 v41, -v39, v40, 1.0
	v_fmac_f32_e32 v40, v41, v40
	v_div_scale_f32 v41, vcc, v33, v38, v33
	v_mul_f32_e32 v42, v41, v40
	v_fma_f32 v43, -v39, v42, v41
	v_fmac_f32_e32 v42, v43, v40
	v_fma_f32 v39, -v39, v42, v41
	v_div_fmas_f32 v39, v39, v40, v42
	v_div_fixup_f32 v33, v39, v38, v33
	v_mul_f32_e32 v27, v27, v33
	v_cvt_pk_bf16_f32 v25, v26, v27
	v_lshl_add_u64 v[26:27], v[28:29], 0, v[2:3]
	v_mov_b32_e32 v104, v24
	v_mov_b32_e32 v105, v25
	s_nop 0
	s_waitcnt vmcnt(8)
	v_mov_b32_e32 v24, v188
	v_mov_b32_e32 v25, v189
	v_lshlrev_b32_e32 v30, 16, v24
	v_mul_f32_e32 v20, v20, v30
	s_waitcnt vmcnt(7)
	v_mov_b32_e32 v26, v214
	v_mov_b32_e32 v27, v215
	v_lshlrev_b32_e32 v30, 16, v26
	v_mul_f32_e32 v31, 0xbfb8aa3b, v30
	v_exp_f32_e32 v31, v31
	v_and_b32_e32 v24, 0xffff0000, v24
	v_mul_f32_e32 v21, v21, v24
	v_and_b32_e32 v24, 0xffff0000, v26
	v_add_f32_e32 v31, 1.0, v31
	v_div_scale_f32 v33, s[0:1], v31, v31, v30
	v_rcp_f32_e32 v34, v33
	v_mul_f32_e32 v26, 0xbfb8aa3b, v24
	v_exp_f32_e32 v26, v26
	v_fma_f32 v35, -v33, v34, 1.0
	v_fmac_f32_e32 v34, v35, v34
	v_div_scale_f32 v35, vcc, v30, v31, v30
	v_mul_f32_e32 v38, v35, v34
	v_fma_f32 v39, -v33, v38, v35
	v_fmac_f32_e32 v38, v39, v34
	v_fma_f32 v33, -v33, v38, v35
	v_div_fmas_f32 v33, v33, v34, v38
	v_div_fixup_f32 v30, v33, v31, v30
	v_add_f32_e32 v26, 1.0, v26
	v_mul_f32_e32 v20, v20, v30
	v_div_scale_f32 v30, s[0:1], v26, v26, v24
	v_rcp_f32_e32 v31, v30
	s_nop 0
	v_fma_f32 v33, -v30, v31, 1.0
	v_fmac_f32_e32 v31, v33, v31
	v_div_scale_f32 v33, vcc, v24, v26, v24
	v_mul_f32_e32 v34, v33, v31
	v_fma_f32 v35, -v30, v34, v33
	v_fmac_f32_e32 v34, v35, v31
	v_fma_f32 v30, -v30, v34, v33
	v_div_fmas_f32 v30, v30, v31, v34
	v_div_fixup_f32 v24, v30, v26, v24
	v_mul_f32_e32 v21, v21, v24
	v_lshlrev_b32_e32 v24, 16, v25
	v_mul_f32_e32 v22, v22, v24
	v_lshlrev_b32_e32 v24, 16, v27
	v_mul_f32_e32 v26, 0xbfb8aa3b, v24
	v_exp_f32_e32 v26, v26
	v_cvt_pk_bf16_f32 v20, v20, v21
	s_nop 0
	v_add_f32_e32 v26, 1.0, v26
	v_div_scale_f32 v30, s[0:1], v26, v26, v24
	v_rcp_f32_e32 v31, v30
	s_nop 0
	v_fma_f32 v33, -v30, v31, 1.0
	v_fmac_f32_e32 v31, v33, v31
	v_div_scale_f32 v33, vcc, v24, v26, v24
	v_mul_f32_e32 v34, v33, v31
	v_fma_f32 v35, -v30, v34, v33
	v_fmac_f32_e32 v34, v35, v31
	v_fma_f32 v30, -v30, v34, v33
	v_div_fmas_f32 v30, v30, v31, v34
	v_div_fixup_f32 v24, v30, v26, v24
	v_mul_f32_e32 v22, v22, v24
	v_and_b32_e32 v24, 0xffff0000, v25
	v_mul_f32_e32 v23, v23, v24
	v_and_b32_e32 v24, 0xffff0000, v27
	v_mul_f32_e32 v25, 0xbfb8aa3b, v24
	v_exp_f32_e32 v25, v25
	s_nop 0
	v_add_f32_e32 v25, 1.0, v25
	v_div_scale_f32 v26, s[0:1], v25, v25, v24
	v_rcp_f32_e32 v27, v26
	s_nop 0
	v_fma_f32 v30, -v26, v27, 1.0
	v_fmac_f32_e32 v27, v30, v27
	v_div_scale_f32 v30, vcc, v24, v25, v24
	v_mul_f32_e32 v31, v30, v27
	v_fma_f32 v32, -v26, v31, v30
	v_fmac_f32_e32 v31, v32, v27
	v_fma_f32 v26, -v26, v31, v30
	v_div_fmas_f32 v26, v26, v27, v31
	v_div_fixup_f32 v24, v26, v25, v24
	v_mul_f32_e32 v23, v23, v24
	v_cvt_pk_bf16_f32 v21, v22, v23
	v_lshl_add_u64 v[22:23], v[28:29], 0, v[60:61]
	v_mov_b32_e32 v106, v20
	v_mov_b32_e32 v107, v21
	global_store_dwordx4 v[22:23], v[104:107], off offset:-8
	v_add_u32_e32 v20, 0x60, v0
	v_mov_b32_e32 v21, v1
	v_lshlrev_b64 v[22:23], 11, v[20:21]
	v_lshl_add_u64 v[26:27], s[86:87], 0, v[22:23]
	v_lshl_add_u64 v[22:23], s[34:35], 0, v[22:23]
	v_lshl_add_u64 v[26:27], v[26:27], 0, v[2:3]
	v_lshl_add_u64 v[22:23], v[22:23], 0, v[2:3]
	v_lshlrev_b64 v[20:21], 12, v[20:21]
	v_lshl_add_u64 v[20:21], s[58:59], 0, v[20:21]
	v_lshl_add_u64 v[20:21], v[20:21], 0, s[6:7]
	v_add_u32_e32 v0, 0x70, v0
	s_waitcnt vmcnt(7)
; __device__ __forceinline__ unsigned cvt_pk_bf16(float lo, float hi) { unsigned r; asm("v_cvt_pk_bf16_f32 %0, %1, %2" : "=v"(r) : "v"(lo), "v"(hi)); return r; }
; __device__ __forceinline__ float bflo(unsigned w) { return __uint_as_float(w << 16); }
; __device__ __forceinline__ float bfhi(unsigned w) { return __uint_as_float(w & 0xffff0000u); }
; __device__ __forceinline__ float silu(float x) { return x / (1.f + __expf(-x)); }
; __device__ __forceinline__ void gmlp_item(const Params& p, int l, int mc, int g, LAS unsigned char* lds) {
;     ...
;     const float* bsp = p.b_s + (size_t)(l * 4 + g) * 128;
; #pragma unroll
;     for (int tt = 0; tt < 8; ++tt) {
;         if (tt < ntt) {
;             const int tok = tok0 + tt * 16 + fr; const float bs = bsp[tt * 16 + fr];
; #pragma unroll
;             for (int ct = 0; ct < 2; ++ct) {
;                 const int cb = g * 256 + w * 32 + ct * 16 + fq * 4;
;                 const u32x2 uu = *(const u32x2*)((const u16*)(ws + WS_ZU) + (size_t)tok * 1024 + cb);
;                 const u32x2 gg = *(const u32x2*)((const u16*)(ws + WS_ZGB) + (size_t)tok * 1024 + cb);
;                 const float o0 = bflo(uu.x) * (acc[ct][tt][0] + bs) * silu(bflo(gg.x));
;                 const float o1 = bfhi(uu.x) * (acc[ct][tt][1] + bs) * silu(bfhi(gg.x));
;                 const float o2 = bflo(uu.y) * (acc[ct][tt][2] + bs) * silu(bflo(gg.y));
;                 const float o3 = bfhi(uu.y) * (acc[ct][tt][3] + bs) * silu(bfhi(gg.y));
;                 u32x2 wv; wv.x = cvt_pk_bf16(o0, o1); wv.y = cvt_pk_bf16(o2, o3);
;                 *(u32x2*)((u16*)(ws + WS_OBUF) + (size_t)tok * 2048 + 1024 + cb) = wv;
	v_mov_b32_e32 v24, v180
	v_add_f32_e32 v16, v16, v24
	s_waitcnt vmcnt(6)
	v_mov_b32_e32 v28, v190
	v_mov_b32_e32 v29, v191
	v_lshlrev_b32_e32 v25, 16, v28
	v_mul_f32_e32 v16, v16, v25
	s_waitcnt vmcnt(5)
	v_mov_b32_e32 v30, v216
	v_mov_b32_e32 v31, v217
	v_lshlrev_b32_e32 v25, 16, v30
	v_mul_f32_e32 v32, 0xbfb8aa3b, v25
	v_exp_f32_e32 v32, v32
	v_add_f32_e32 v17, v17, v24
	v_add_f32_e32 v18, v18, v24
	v_add_f32_e32 v19, v19, v24
	v_add_f32_e32 v32, 1.0, v32
	v_div_scale_f32 v33, s[0:1], v32, v32, v25
	v_rcp_f32_e32 v34, v33
	v_add_f32_e32 v12, v12, v24
	v_add_f32_e32 v13, v13, v24
	v_add_f32_e32 v14, v14, v24
	v_fma_f32 v35, -v33, v34, 1.0
	v_fmac_f32_e32 v34, v35, v34
	v_div_scale_f32 v35, vcc, v25, v32, v25
	v_mul_f32_e32 v38, v35, v34
	v_fma_f32 v39, -v33, v38, v35
	v_fmac_f32_e32 v38, v39, v34
	v_fma_f32 v33, -v33, v38, v35
	v_div_fmas_f32 v33, v33, v34, v38
	v_div_fixup_f32 v25, v33, v32, v25
	v_mul_f32_e32 v16, v16, v25
	v_and_b32_e32 v25, 0xffff0000, v28
	v_mul_f32_e32 v17, v17, v25
	v_and_b32_e32 v25, 0xffff0000, v30
	v_mul_f32_e32 v28, 0xbfb8aa3b, v25
	v_exp_f32_e32 v28, v28
	v_add_f32_e32 v15, v15, v24
	v_add_f32_e32 v28, 1.0, v28
	v_div_scale_f32 v30, s[0:1], v28, v28, v25
	v_rcp_f32_e32 v32, v30
	s_nop 0
	v_fma_f32 v33, -v30, v32, 1.0
	v_fmac_f32_e32 v32, v33, v32
	v_div_scale_f32 v33, vcc, v25, v28, v25
	v_mul_f32_e32 v34, v33, v32
	v_fma_f32 v35, -v30, v34, v33
	v_fmac_f32_e32 v34, v35, v32
	v_fma_f32 v30, -v30, v34, v33
	v_div_fmas_f32 v30, v30, v32, v34
	v_div_fixup_f32 v25, v30, v28, v25
	v_mul_f32_e32 v17, v17, v25
	v_lshlrev_b32_e32 v25, 16, v29
	v_mul_f32_e32 v18, v18, v25
	v_lshlrev_b32_e32 v25, 16, v31
	v_mul_f32_e32 v28, 0xbfb8aa3b, v25
	v_exp_f32_e32 v28, v28
	v_cvt_pk_bf16_f32 v16, v16, v17
	s_nop 0
	v_add_f32_e32 v28, 1.0, v28
	v_div_scale_f32 v30, s[0:1], v28, v28, v25
	v_rcp_f32_e32 v32, v30
	s_nop 0
	v_fma_f32 v33, -v30, v32, 1.0
	v_fmac_f32_e32 v32, v33, v32
	v_div_scale_f32 v33, vcc, v25, v28, v25
	v_mul_f32_e32 v34, v33, v32
	v_fma_f32 v35, -v30, v34, v33
	v_fmac_f32_e32 v34, v35, v32
	v_fma_f32 v30, -v30, v34, v33
	v_div_fmas_f32 v30, v30, v32, v34
	v_div_fixup_f32 v25, v30, v28, v25
	v_mul_f32_e32 v18, v18, v25
	v_and_b32_e32 v25, 0xffff0000, v29
	v_mul_f32_e32 v19, v19, v25
	v_and_b32_e32 v25, 0xffff0000, v31
	v_mul_f32_e32 v28, 0xbfb8aa3b, v25
	v_exp_f32_e32 v28, v28
	s_nop 0
	v_add_f32_e32 v28, 1.0, v28
	v_div_scale_f32 v29, s[0:1], v28, v28, v25
	v_rcp_f32_e32 v30, v29
	s_nop 0
	v_fma_f32 v31, -v29, v30, 1.0
	v_fmac_f32_e32 v30, v31, v30
	v_div_scale_f32 v31, vcc, v25, v28, v25
	v_mul_f32_e32 v32, v31, v30
	v_fma_f32 v33, -v29, v32, v31
	v_fmac_f32_e32 v32, v33, v30
	v_fma_f32 v29, -v29, v32, v31
	v_div_fmas_f32 v29, v29, v30, v32
	v_div_fixup_f32 v25, v29, v28, v25
	v_mul_f32_e32 v19, v19, v25
	v_cvt_pk_bf16_f32 v17, v18, v19
	v_lshl_add_u64 v[18:19], v[20:21], 0, v[2:3]
	v_mov_b32_e32 v104, v16
	v_mov_b32_e32 v105, v17
	s_nop 0
	s_waitcnt vmcnt(6)
	v_mov_b32_e32 v16, v192
	v_mov_b32_e32 v17, v193
	v_lshlrev_b32_e32 v22, 16, v16
	v_mul_f32_e32 v12, v12, v22
	s_waitcnt vmcnt(5)
	v_mov_b32_e32 v18, v218
	v_mov_b32_e32 v19, v219
	v_lshlrev_b32_e32 v22, 16, v18
	v_mul_f32_e32 v23, 0xbfb8aa3b, v22
	v_exp_f32_e32 v23, v23
	v_and_b32_e32 v16, 0xffff0000, v16
	v_mul_f32_e32 v13, v13, v16
	v_and_b32_e32 v16, 0xffff0000, v18
	v_add_f32_e32 v23, 1.0, v23
	v_div_scale_f32 v25, s[0:1], v23, v23, v22
	v_rcp_f32_e32 v26, v25
	v_mul_f32_e32 v18, 0xbfb8aa3b, v16
	v_exp_f32_e32 v18, v18
	v_fma_f32 v27, -v25, v26, 1.0
	v_fmac_f32_e32 v26, v27, v26
	v_div_scale_f32 v27, vcc, v22, v23, v22
	v_mul_f32_e32 v28, v27, v26
	v_fma_f32 v29, -v25, v28, v27
	v_fmac_f32_e32 v28, v29, v26
	v_fma_f32 v25, -v25, v28, v27
	v_div_fmas_f32 v25, v25, v26, v28
	v_div_fixup_f32 v22, v25, v23, v22
	v_add_f32_e32 v18, 1.0, v18
	v_mul_f32_e32 v12, v12, v22
	v_div_scale_f32 v22, s[0:1], v18, v18, v16
	v_rcp_f32_e32 v23, v22
	s_nop 0
	v_fma_f32 v25, -v22, v23, 1.0
	v_fmac_f32_e32 v23, v25, v23
	v_div_scale_f32 v25, vcc, v16, v18, v16
	v_mul_f32_e32 v26, v25, v23
	v_fma_f32 v27, -v22, v26, v25
	v_fmac_f32_e32 v26, v27, v23
	v_fma_f32 v22, -v22, v26, v25
	v_div_fmas_f32 v22, v22, v23, v26
	v_div_fixup_f32 v16, v22, v18, v16
	v_mul_f32_e32 v13, v13, v16
	v_lshlrev_b32_e32 v16, 16, v17
	v_mul_f32_e32 v14, v14, v16
	v_lshlrev_b32_e32 v16, 16, v19
	v_mul_f32_e32 v18, 0xbfb8aa3b, v16
	v_exp_f32_e32 v18, v18
	v_cvt_pk_bf16_f32 v12, v12, v13
	s_nop 0
	v_add_f32_e32 v18, 1.0, v18
	v_div_scale_f32 v22, s[0:1], v18, v18, v16
	v_rcp_f32_e32 v23, v22
	s_nop 0
	v_fma_f32 v25, -v22, v23, 1.0
	v_fmac_f32_e32 v23, v25, v23
	v_div_scale_f32 v25, vcc, v16, v18, v16
	v_mul_f32_e32 v26, v25, v23
	v_fma_f32 v27, -v22, v26, v25
	v_fmac_f32_e32 v26, v27, v23
	v_fma_f32 v22, -v22, v26, v25
	v_div_fmas_f32 v22, v22, v23, v26
	v_div_fixup_f32 v16, v22, v18, v16
	v_mul_f32_e32 v14, v14, v16
	v_and_b32_e32 v16, 0xffff0000, v17
	v_mul_f32_e32 v15, v15, v16
	v_and_b32_e32 v16, 0xffff0000, v19
	v_mul_f32_e32 v17, 0xbfb8aa3b, v16
	v_exp_f32_e32 v17, v17
	s_nop 0
	v_add_f32_e32 v17, 1.0, v17
	v_div_scale_f32 v18, s[0:1], v17, v17, v16
	v_rcp_f32_e32 v19, v18
	s_nop 0
	v_fma_f32 v22, -v18, v19, 1.0
	v_fmac_f32_e32 v19, v22, v19
	v_div_scale_f32 v22, vcc, v16, v17, v16
	v_mul_f32_e32 v23, v22, v19
	v_fma_f32 v24, -v18, v23, v22
	v_fmac_f32_e32 v23, v24, v19
	v_fma_f32 v18, -v18, v23, v22
	v_div_fmas_f32 v18, v18, v19, v23
	v_div_fixup_f32 v16, v18, v17, v16
	v_mul_f32_e32 v15, v15, v16
	v_cvt_pk_bf16_f32 v13, v14, v15
	v_lshl_add_u64 v[14:15], v[20:21], 0, v[60:61]
	v_mov_b32_e32 v106, v12
	v_mov_b32_e32 v107, v13
	global_store_dwordx4 v[14:15], v[104:107], off offset:-8
	v_lshlrev_b64 v[12:13], 11, v[0:1]
	v_lshl_add_u64 v[14:15], s[86:87], 0, v[12:13]
	v_lshl_add_u64 v[18:19], s[34:35], 0, v[12:13]
	v_lshl_add_u64 v[20:21], v[14:15], 0, v[2:3]
	v_lshl_add_u64 v[14:15], v[18:19], 0, v[2:3]
	v_lshlrev_b64 v[12:13], 12, v[0:1]
	v_lshl_add_u64 v[12:13], s[58:59], 0, v[12:13]
	v_lshl_add_u64 v[12:13], v[12:13], 0, s[6:7]
	v_lshl_add_u64 v[2:3], v[12:13], 0, v[2:3]
	s_waitcnt vmcnt(5)
; __device__ __forceinline__ unsigned cvt_pk_bf16(float lo, float hi) { unsigned r; asm("v_cvt_pk_bf16_f32 %0, %1, %2" : "=v"(r) : "v"(lo), "v"(hi)); return r; }
; __device__ __forceinline__ float bflo(unsigned w) { return __uint_as_float(w << 16); }
; __device__ __forceinline__ float bfhi(unsigned w) { return __uint_as_float(w & 0xffff0000u); }
; __device__ __forceinline__ float silu(float x) { return x / (1.f + __expf(-x)); }
; __device__ __forceinline__ void gmlp_item(const Params& p, int l, int mc, int g, LAS unsigned char* lds) {
;     ...
;     const float* bsp = p.b_s + (size_t)(l * 4 + g) * 128;
; #pragma unroll
;     for (int tt = 0; tt < 8; ++tt) {
;         if (tt < ntt) {
;             const int tok = tok0 + tt * 16 + fr; const float bs = bsp[tt * 16 + fr];
; #pragma unroll
;             for (int ct = 0; ct < 2; ++ct) {
;                 const int cb = g * 256 + w * 32 + ct * 16 + fq * 4;
;                 const u32x2 uu = *(const u32x2*)((const u16*)(ws + WS_ZU) + (size_t)tok * 1024 + cb);
;                 const u32x2 gg = *(const u32x2*)((const u16*)(ws + WS_ZGB) + (size_t)tok * 1024 + cb);
;                 const float o0 = bflo(uu.x) * (acc[ct][tt][0] + bs) * silu(bflo(gg.x));
;                 const float o1 = bfhi(uu.x) * (acc[ct][tt][1] + bs) * silu(bfhi(gg.x));
;                 const float o2 = bflo(uu.y) * (acc[ct][tt][2] + bs) * silu(bflo(gg.y));
;                 const float o3 = bfhi(uu.y) * (acc[ct][tt][3] + bs) * silu(bfhi(gg.y));
;                 u32x2 wv; wv.x = cvt_pk_bf16(o0, o1); wv.y = cvt_pk_bf16(o2, o3);
;                 *(u32x2*)((u16*)(ws + WS_OBUF) + (size_t)tok * 2048 + 1024 + cb) = wv;
	v_mov_b32_e32 v16, v181
	v_add_f32_e32 v8, v8, v16
	s_waitcnt vmcnt(4)
	v_mov_b32_e32 v22, v194
	v_mov_b32_e32 v23, v195
	v_lshlrev_b32_e32 v0, 16, v22
	v_mul_f32_e32 v0, v8, v0
	s_waitcnt vmcnt(3)
	v_mov_b32_e32 v18, v220
	v_mov_b32_e32 v19, v221
	v_lshlrev_b32_e32 v8, 16, v18
	v_mul_f32_e32 v17, 0xbfb8aa3b, v8
	v_exp_f32_e32 v17, v17
	v_add_f32_e32 v9, v9, v16
	v_add_f32_e32 v10, v10, v16
	v_add_f32_e32 v11, v11, v16
	v_add_f32_e32 v17, 1.0, v17
	v_div_scale_f32 v24, s[0:1], v17, v17, v8
	v_rcp_f32_e32 v25, v24
	v_add_f32_e32 v4, v4, v16
	v_fma_f32 v26, -v24, v25, 1.0
	v_fmac_f32_e32 v25, v26, v25
	v_div_scale_f32 v26, vcc, v8, v17, v8
	v_mul_f32_e32 v27, v26, v25
	v_fma_f32 v28, -v24, v27, v26
	v_fmac_f32_e32 v27, v28, v25
	v_fma_f32 v24, -v24, v27, v26
	v_div_fmas_f32 v24, v24, v25, v27
	v_div_fixup_f32 v8, v24, v17, v8
	v_mul_f32_e32 v0, v0, v8
	v_and_b32_e32 v8, 0xffff0000, v22
	v_mul_f32_e32 v8, v9, v8
	v_and_b32_e32 v9, 0xffff0000, v18
	v_mul_f32_e32 v17, 0xbfb8aa3b, v9
	v_exp_f32_e32 v17, v17
	s_nop 0
	v_add_f32_e32 v17, 1.0, v17
	v_div_scale_f32 v18, s[0:1], v17, v17, v9
	v_rcp_f32_e32 v22, v18
	s_nop 0
	v_fma_f32 v24, -v18, v22, 1.0
	v_fmac_f32_e32 v22, v24, v22
	v_div_scale_f32 v24, vcc, v9, v17, v9
	v_mul_f32_e32 v25, v24, v22
	v_fma_f32 v26, -v18, v25, v24
	v_fmac_f32_e32 v25, v26, v22
	v_fma_f32 v18, -v18, v25, v24
	v_div_fmas_f32 v18, v18, v22, v25
	v_div_fixup_f32 v9, v18, v17, v9
	v_mul_f32_e32 v8, v8, v9
	v_lshlrev_b32_e32 v9, 16, v23
	v_mul_f32_e32 v9, v10, v9
	v_lshlrev_b32_e32 v10, 16, v19
	v_mul_f32_e32 v17, 0xbfb8aa3b, v10
	v_exp_f32_e32 v17, v17
	v_cvt_pk_bf16_f32 v8, v0, v8
	s_nop 0
	v_add_f32_e32 v17, 1.0, v17
	v_div_scale_f32 v18, s[0:1], v17, v17, v10
	v_rcp_f32_e32 v22, v18
	s_nop 0
	v_fma_f32 v24, -v18, v22, 1.0
	v_fmac_f32_e32 v22, v24, v22
	v_div_scale_f32 v24, vcc, v10, v17, v10
	v_mul_f32_e32 v25, v24, v22
	v_fma_f32 v26, -v18, v25, v24
	v_fmac_f32_e32 v25, v26, v22
	v_fma_f32 v18, -v18, v25, v24
	v_div_fmas_f32 v18, v18, v22, v25
	v_div_fixup_f32 v10, v18, v17, v10
	v_mul_f32_e32 v9, v9, v10
	v_and_b32_e32 v10, 0xffff0000, v23
	v_mul_f32_e32 v10, v11, v10
	v_and_b32_e32 v11, 0xffff0000, v19
	v_mul_f32_e32 v17, 0xbfb8aa3b, v11
	v_exp_f32_e32 v17, v17
	s_nop 0
	v_add_f32_e32 v17, 1.0, v17
	v_div_scale_f32 v18, s[0:1], v17, v17, v11
	v_rcp_f32_e32 v19, v18
	s_nop 0
	v_fma_f32 v22, -v18, v19, 1.0
	v_fmac_f32_e32 v19, v22, v19
	v_div_scale_f32 v22, vcc, v11, v17, v11
	v_mul_f32_e32 v23, v22, v19
	v_fma_f32 v24, -v18, v23, v22
	v_fmac_f32_e32 v23, v24, v19
	v_fma_f32 v18, -v18, v23, v22
	v_div_fmas_f32 v18, v18, v19, v23
	v_div_fixup_f32 v11, v18, v17, v11
	v_mul_f32_e32 v10, v10, v11
	v_cvt_pk_bf16_f32 v9, v9, v10
	v_mov_b32_e32 v104, v8
	v_mov_b32_e32 v105, v9
	s_nop 0
	s_waitcnt vmcnt(4)
	v_mov_b32_e32 v2, v196
	v_mov_b32_e32 v3, v197
	v_lshlrev_b32_e32 v0, 16, v2
	v_mul_f32_e32 v0, v4, v0
	s_waitcnt vmcnt(3)
	v_mov_b32_e32 v8, v222
	v_mov_b32_e32 v9, v223
	v_lshlrev_b32_e32 v4, 16, v8
	v_mul_f32_e32 v10, 0xbfb8aa3b, v4
	v_exp_f32_e32 v10, v10
	v_and_b32_e32 v2, 0xffff0000, v2
	v_add_f32_e32 v10, 1.0, v10
	v_div_scale_f32 v11, s[0:1], v10, v10, v4
	v_rcp_f32_e32 v14, v11
	s_nop 0
	v_fma_f32 v15, -v11, v14, 1.0
	v_fmac_f32_e32 v14, v15, v14
	v_div_scale_f32 v15, vcc, v4, v10, v4
	v_mul_f32_e32 v17, v15, v14
	v_fma_f32 v18, -v11, v17, v15
	v_fmac_f32_e32 v17, v18, v14
	v_fma_f32 v11, -v11, v17, v15
	v_div_fmas_f32 v11, v11, v14, v17
	v_div_fixup_f32 v4, v11, v10, v4
	v_mul_f32_e32 v0, v0, v4
	v_add_f32_e32 v4, v5, v16
	v_mul_f32_e32 v2, v4, v2
	v_and_b32_e32 v4, 0xffff0000, v8
	v_mul_f32_e32 v5, 0xbfb8aa3b, v4
	v_exp_f32_e32 v5, v5
	s_nop 0
	v_add_f32_e32 v5, 1.0, v5
	v_div_scale_f32 v8, s[0:1], v5, v5, v4
	v_rcp_f32_e32 v10, v8
	s_nop 0
	v_fma_f32 v11, -v8, v10, 1.0
	v_fmac_f32_e32 v10, v11, v10
	v_div_scale_f32 v11, vcc, v4, v5, v4
	v_mul_f32_e32 v14, v11, v10
	v_fma_f32 v15, -v8, v14, v11
	v_fmac_f32_e32 v14, v15, v10
	v_fma_f32 v8, -v8, v14, v11
	v_div_fmas_f32 v8, v8, v10, v14
	v_div_fixup_f32 v4, v8, v5, v4
	v_mul_f32_e32 v2, v2, v4
	v_lshlrev_b32_e32 v4, 16, v3
	v_add_f32_e32 v5, v6, v16
	v_mul_f32_e32 v4, v5, v4
	v_lshlrev_b32_e32 v5, 16, v9
	v_mul_f32_e32 v6, 0xbfb8aa3b, v5
	v_exp_f32_e32 v6, v6
	v_and_b32_e32 v3, 0xffff0000, v3
	v_cvt_pk_bf16_f32 v2, v0, v2
	v_add_f32_e32 v6, 1.0, v6
	v_div_scale_f32 v8, s[0:1], v6, v6, v5
	v_rcp_f32_e32 v10, v8
	s_nop 0
	v_fma_f32 v11, -v8, v10, 1.0
	v_fmac_f32_e32 v10, v11, v10
	v_div_scale_f32 v11, vcc, v5, v6, v5
	v_mul_f32_e32 v14, v11, v10
	v_fma_f32 v15, -v8, v14, v11
	v_fmac_f32_e32 v14, v15, v10
	v_fma_f32 v8, -v8, v14, v11
	v_div_fmas_f32 v8, v8, v10, v14
	v_div_fixup_f32 v5, v8, v6, v5
	v_mul_f32_e32 v4, v4, v5
	v_add_f32_e32 v5, v7, v16
	v_mul_f32_e32 v3, v5, v3
	v_and_b32_e32 v5, 0xffff0000, v9
	v_mul_f32_e32 v6, 0xbfb8aa3b, v5
	v_exp_f32_e32 v6, v6
	s_nop 0
	v_add_f32_e32 v6, 1.0, v6
	v_div_scale_f32 v7, s[0:1], v6, v6, v5
	v_rcp_f32_e32 v8, v7
	s_nop 0
	v_fma_f32 v9, -v7, v8, 1.0
	v_fmac_f32_e32 v8, v9, v8
	v_div_scale_f32 v9, vcc, v5, v6, v5
	v_mul_f32_e32 v10, v9, v8
	v_fma_f32 v11, -v7, v10, v9
	v_fmac_f32_e32 v10, v11, v8
	v_fma_f32 v7, -v7, v10, v9
	v_div_fmas_f32 v7, v7, v8, v10
	v_div_fixup_f32 v5, v7, v6, v5
	v_mul_f32_e32 v3, v3, v5
	v_cvt_pk_bf16_f32 v3, v4, v3
	v_lshl_add_u64 v[4:5], v[12:13], 0, v[60:61]
	v_mov_b32_e32 v106, v2
	v_mov_b32_e32 v107, v3
	global_store_dwordx4 v[4:5], v[104:107], off offset:-8

; #define LAS __attribute__((address_space(3)))
; __device__ __forceinline__ void gmlp_item(const Params& p, int l, int mc, int g, LAS unsigned char* lds) {
;     ...
;     for (int kk = 0; kk < 4; ++kk) {
;         bf16x8 a[2];
; #pragma unroll
;         for (int ct = 0; ct < 2; ++ct) a[ct] = *(const LAS bf16x8*)(Vn + (w * 32 + ct * 16 + fr) * 272 + (kk * 32 + fq * 8) * 2);
; #pragma unroll
;         for (int tt = 0; tt < 8; ++tt) {
;             if ((tt >> 1) >= kk && tt < ntt) {
;                 const bf16x8 bw = *(const LAS bf16x8*)(Wl + (tt * 16 + fr) * 272 + (kk * 32 + fq * 8) * 2);
; #pragma unroll
;                 for (int ct = 0; ct < 2; ++ct) acc[ct][tt] = __builtin_amdgcn_mfma_f32_16x16x32_bf16(a[ct], bw, acc[ct][tt], 0, 0, 0);
;             }
.LBB0_778:
	ds_read_b128 v[68:71], v86 offset:30528
	s_waitcnt lgkmcnt(0)
	v_mfma_f32_16x16x32_bf16 v[8:11], v[76:79], v[68:71], v[8:11]
	v_mfma_f32_16x16x32_bf16 v[4:7], v[80:83], v[68:71], v[4:7]
	ds_read_b128 v[68:71], v85 offset:4224
	ds_read_b128 v[72:75], v85 offset:5312
	s_and_b64 vcc, exec, s[38:39]
	s_cbranch_vccnz .LBB0_760

; #define LAS __attribute__((address_space(3)))
; __device__ __forceinline__ void gmlp_item(const Params& p, int l, int mc, int g, LAS unsigned char* lds) {
;     ...
;     for (int kk = 0; kk < 4; ++kk) {
;         bf16x8 a[2];
; #pragma unroll
;         for (int ct = 0; ct < 2; ++ct) a[ct] = *(const LAS bf16x8*)(Vn + (w * 32 + ct * 16 + fr) * 272 + (kk * 32 + fq * 8) * 2);
; #pragma unroll
;         for (int tt = 0; tt < 8; ++tt) {
;             if ((tt >> 1) >= kk && tt < ntt) {
;                 const bf16x8 bw = *(const LAS bf16x8*)(Wl + (tt * 16 + fr) * 272 + (kk * 32 + fq * 8) * 2);
; #pragma unroll
;                 for (int ct = 0; ct < 2; ++ct) acc[ct][tt] = __builtin_amdgcn_mfma_f32_16x16x32_bf16(a[ct], bw, acc[ct][tt], 0, 0, 0);
;             }
.LBB0_782:
	ds_read_b128 v[76:79], v86 offset:30592
	s_waitcnt lgkmcnt(0)
	v_mfma_f32_16x16x32_bf16 v[8:11], v[68:71], v[76:79], v[8:11]
	v_mfma_f32_16x16x32_bf16 v[4:7], v[72:75], v[76:79], v[4:7]
	ds_read_b128 v[68:71], v85 offset:4288
	ds_read_b128 v[72:75], v85 offset:5376
	s_and_b64 vcc, exec, s[38:39]
	s_cbranch_vccnz .LBB0_764
